# sample WKV scan rewritten: operands of the 4 steps loaded/unpacked once per (batch,head) and reused over 8 row groups, all state tiles prefetched, y gathered through LDS into one 16B store per lane
# speedup vs baseline: 1.0198x; 1.0107x over previous
; __device__ __forceinline__ float bf2f(bf16_t h) { return __uint_as_float((unsigned)h << 16); }
; __device__ __forceinline__ f32x4 unpack4(const u32x2 w) { return (f32x4){__uint_as_float(w[0] << 16), __uint_as_float(w[0] & 0xffff0000u), __uint_as_float(w[1] << 16), __uint_as_float(w[1] & 0xffff0000u)}; }
; __device__ __forceinline__ void scan_wkv_sample(PP P, int l, const Ids I) {
;     ...
;     for (int q = gw; q < 128 * 8 * 16; q += nw) {
;         const int pair = q >> 4, rgp = q & 15, sb = pair >> 3, h = pair & 7, vrow = rgp * 4 + rowl;
;         const unsigned so = ((unsigned)((l * 128 + sb) * 8 + h) * 64u + vrow) * 64u + kseg * 4;
;         f32x4 S = *(const f32x4*)(sin_ + so);
;         f32x4 r_[4], w_[4], k_[4], a_[4], b_[4]; float v_[4];
; #pragma unroll
;         for (int s = 0; s < 4; ++s) { const unsigned row = (unsigned)MTP + sb * 4 + s, o = row * 512u + h * 64 + kseg * 4;
;             r_[s] = unpack4(*(const u32x2*)(arr + A_R * AS + o)); w_[s] = unpack4(*(const u32x2*)(arr + A_EW * AS + o)); k_[s] = unpack4(*(const u32x2*)(arr + A_KF * AS + o));
;             a_[s] = unpack4(*(const u32x2*)(arr + A_KK * AS + o)); b_[s] = unpack4(*(const u32x2*)(arr + A_BB * AS + o)); v_[s] = bf2f(arr[A_V * AS + row * 512u + h * 64 + vrow]); }
.LBB0_59:
	v_writelane_b32 v254, s36, 50
	s_nop 1
	v_writelane_b32 v254, s37, 51
	v_writelane_b32 v254, s18, 48
	v_writelane_b32 v254, s25, 49
	v_writelane_b32 v254, s47, 54
	s_or_b64 exec, exec, s[6:7]
	v_readlane_b32 s16, v254, 34
	v_writelane_b32 v254, s85, 61
	v_mbcnt_lo_u32_b32 v0, -1, 0
	v_mbcnt_hi_u32_b32 v0, -1, v0
	v_writelane_b32 v254, s67, 62
	v_add_u32_e32 v1, s62, v0
	s_nop 0
	v_readfirstlane_b32 s0, v1
	s_ashr_i32 s1, s0, 6
	v_readlane_b32 s0, v254, 29
	s_add_i32 s0, s1, s0
	s_cmpk_lt_i32 s0, 0x4000
	s_cbranch_scc0 .LBB0_754
	s_waitcnt lgkmcnt(0)
	s_add_u32 s4, s12, 0x47fc000
	s_addc_u32 s5, s13, 0
	s_load_dwordx2 s[6:7], s[88:89], 0x38
	v_bfe_u32 v34, v0, 4, 2
	v_and_b32_e32 v33, 15, v0
	v_lshlrev_b32_e32 v35, 2, v33
	s_lshr_b32 s8, s0, 4
	s_bfe_u32 s9, s0, 0x30001
	s_and_b32 s1, s0, 1
	s_lshl_b32 s1, s1, 5
	s_lshl_b32 s3, s8, 2
	s_add_i32 s13, s3, 0x4000
	s_lshl_b32 s12, s9, 6
	v_readlane_b32 s14, v254, 35
	v_readlane_b32 s15, v254, 36
	v_readlane_b32 s18, v254, 37
	v_readlane_b32 s19, v254, 38
	v_mov_b32_e32 v9, 0
	s_lshl_b32 s3, s13, 9
	v_or_b32_e32 v8, s12, v35
	v_or_b32_e32 v8, s3, v8
	v_lshl_add_u64 v[10:11], v[8:9], 1, s[14:15]
	global_load_dwordx2 v[108:109], v[10:11], off
	global_load_dwordx2 v[110:111], v[10:11], off offset:1024
	global_load_dwordx2 v[112:113], v[10:11], off offset:2048
	global_load_dwordx2 v[114:115], v[10:11], off offset:3072
	s_nop 0
	v_lshl_add_u64 v[10:11], v[8:9], 1, s[74:75]
	global_load_dwordx2 v[116:117], v[10:11], off
	global_load_dwordx2 v[118:119], v[10:11], off offset:1024
	global_load_dwordx2 v[120:121], v[10:11], off offset:2048
	global_load_dwordx2 v[122:123], v[10:11], off offset:3072
	s_nop 0
	v_lshl_add_u64 v[10:11], v[8:9], 1, s[18:19]
	global_load_dwordx2 v[124:125], v[10:11], off
	global_load_dwordx2 v[126:127], v[10:11], off offset:1024
	global_load_dwordx2 v[128:129], v[10:11], off offset:2048
	global_load_dwordx2 v[130:131], v[10:11], off offset:3072
	s_nop 0
	v_lshl_add_u64 v[10:11], v[8:9], 1, s[52:53]
	global_load_dwordx2 v[132:133], v[10:11], off
	global_load_dwordx2 v[134:135], v[10:11], off offset:1024
	global_load_dwordx2 v[136:137], v[10:11], off offset:2048
	global_load_dwordx2 v[138:139], v[10:11], off offset:3072
	s_nop 0
	v_lshl_add_u64 v[10:11], v[8:9], 1, s[70:71]
	global_load_dwordx2 v[140:141], v[10:11], off
	global_load_dwordx2 v[142:143], v[10:11], off offset:1024
	global_load_dwordx2 v[246:247], v[10:11], off offset:2048
	global_load_dwordx2 v[248:249], v[10:11], off offset:3072
	s_nop 0
	v_add_u32_e32 v49, s1, v34
	s_lshl_b32 s3, s8, 3
	s_add_i32 s3, s3, s16
	s_or_b32 s3, s3, s9
	s_lshl_b32 s3, s3, 12
	v_lshlrev_b32_e32 v10, 6, v49
	v_or3_b32 v8, s3, v10, v35
	s_waitcnt lgkmcnt(0)
	v_lshl_add_u64 v[0:1], v[8:9], 2, s[6:7]
	v_lshl_add_u64 v[2:3], v[8:9], 2, s[4:5]
	v_and_b32_e32 v10, 3, v33
	v_add_u32_e32 v8, s13, v10
	v_lshlrev_b32_e32 v8, 9, v8
	v_add3_u32 v8, v8, s12, v49
	v_add_u32_e32 v8, 0x2940000, v8
	v_lshl_add_u64 v[4:5], v[8:9], 1, s[96:97]
	global_load_dwordx4 v[12:15], v[0:1], off
	global_load_ushort v16, v[4:5], off
	global_load_dwordx4 v[54:57], v[0:1], off offset:1024
	global_load_ushort v58, v[4:5], off offset:8
	v_mov_b32_e32 v52, 0x1000
	v_mov_b32_e32 v53, 0
	v_lshl_add_u64 v[50:51], v[0:1], 0, v[52:53]
	v_lshl_add_u64 v[6:7], v[2:3], 0, v[52:53]
	s_and_b32 s3, s0, 7
	s_lshl_b32 s3, s3, 9
	s_add_i32 s3, s3, 0x23000
	v_lshlrev_b32_e32 v17, 7, v33
	v_lshl_add_u32 v17, v34, 2, v17
	v_add_u32_e32 v17, s3, v17
	v_lshrrev_b32_e32 v18, 2, v33
	v_lshlrev_b32_e32 v19, 7, v18
	v_lshl_add_u32 v19, v10, 5, v19
	v_add_u32_e32 v19, s3, v19
	v_add_u32_e32 v8, s13, v18
	v_lshlrev_b32_e32 v8, 10, v8
	s_add_i32 s3, s12, s1
	s_addk_i32 s3, 0x200
	v_lshl_add_u32 v18, v10, 3, v8
	v_add_u32_e32 v8, s3, v18
	v_cmp_eq_u32_e64 s[8:9], 1, v10
	v_cmp_eq_u32_e64 s[12:13], 2, v10
	v_cmp_eq_u32_e64 s[14:15], 3, v10
	v_cmp_gt_u32_e64 s[18:19], 4, v33
	v_lshl_add_u64 v[10:11], v[8:9], 1, s[78:79]
	v_cmp_eq_u32_e64 s[0:1], 0, v34
	s_waitcnt vmcnt(20)
	v_lshlrev_b32_e32 v152, 16, v108
	v_and_b32_e32 v153, 0xffff0000, v108
	v_lshlrev_b32_e32 v154, 16, v109
	v_and_b32_e32 v155, 0xffff0000, v109
	v_lshlrev_b32_e32 v176, 16, v110
	v_and_b32_e32 v177, 0xffff0000, v110
	v_lshlrev_b32_e32 v178, 16, v111
	v_and_b32_e32 v179, 0xffff0000, v111
	v_lshlrev_b32_e32 v200, 16, v112
	v_and_b32_e32 v201, 0xffff0000, v112
	v_lshlrev_b32_e32 v202, 16, v113
	v_and_b32_e32 v203, 0xffff0000, v113
	v_lshlrev_b32_e32 v220, 16, v114
	v_and_b32_e32 v221, 0xffff0000, v114
	v_lshlrev_b32_e32 v222, 16, v115
	v_and_b32_e32 v223, 0xffff0000, v115
	s_waitcnt vmcnt(16)
	v_lshlrev_b32_e32 v156, 16, v116
	v_and_b32_e32 v157, 0xffff0000, v116
	v_lshlrev_b32_e32 v158, 16, v117
	v_and_b32_e32 v159, 0xffff0000, v117
	v_lshlrev_b32_e32 v180, 16, v118
	v_and_b32_e32 v181, 0xffff0000, v118
	v_lshlrev_b32_e32 v182, 16, v119
	v_and_b32_e32 v183, 0xffff0000, v119
	v_lshlrev_b32_e32 v204, 16, v120
	v_and_b32_e32 v205, 0xffff0000, v120
	v_lshlrev_b32_e32 v206, 16, v121
	v_and_b32_e32 v207, 0xffff0000, v121
	v_lshlrev_b32_e32 v224, 16, v122
	v_and_b32_e32 v225, 0xffff0000, v122
	v_lshlrev_b32_e32 v226, 16, v123
	v_and_b32_e32 v227, 0xffff0000, v123
	v_mul_f32_e32 v156, 0xbfb8aa3b, v156
	v_mul_f32_e32 v157, 0xbfb8aa3b, v157
	v_mul_f32_e32 v158, 0xbfb8aa3b, v158
	v_mul_f32_e32 v159, 0xbfb8aa3b, v159
	v_mul_f32_e32 v180, 0xbfb8aa3b, v180
	v_mul_f32_e32 v181, 0xbfb8aa3b, v181
	v_mul_f32_e32 v182, 0xbfb8aa3b, v182
	v_mul_f32_e32 v183, 0xbfb8aa3b, v183
	v_mul_f32_e32 v204, 0xbfb8aa3b, v204
	v_mul_f32_e32 v205, 0xbfb8aa3b, v205
	v_mul_f32_e32 v206, 0xbfb8aa3b, v206
	v_mul_f32_e32 v207, 0xbfb8aa3b, v207
	v_mul_f32_e32 v224, 0xbfb8aa3b, v224
	v_mul_f32_e32 v225, 0xbfb8aa3b, v225
	v_mul_f32_e32 v226, 0xbfb8aa3b, v226
	v_mul_f32_e32 v227, 0xbfb8aa3b, v227
	v_exp_f32_e32 v156, v156
	v_exp_f32_e32 v157, v157
	v_exp_f32_e32 v158, v158
	v_exp_f32_e32 v159, v159
	v_exp_f32_e32 v180, v180
	v_exp_f32_e32 v181, v181
	v_exp_f32_e32 v182, v182
	v_exp_f32_e32 v183, v183
	v_exp_f32_e32 v204, v204
	v_exp_f32_e32 v205, v205
	v_exp_f32_e32 v206, v206
	v_exp_f32_e32 v207, v207
	v_exp_f32_e32 v224, v224
	v_exp_f32_e32 v225, v225
	v_exp_f32_e32 v226, v226
	v_exp_f32_e32 v227, v227
	s_waitcnt vmcnt(12)
; __device__ __forceinline__ float bf2f(bf16_t h) { return __uint_as_float((unsigned)h << 16); }
; __device__ __forceinline__ bf16_t f2bf(float f) { return (bf16_t)(cvt_pk_bf16(f, 0.f) & 0xffffu); }
; __device__ __forceinline__ f32x4 unpack4(const u32x2 w) { return (f32x4){__uint_as_float(w[0] << 16), __uint_as_float(w[0] & 0xffff0000u), __uint_as_float(w[1] << 16), __uint_as_float(w[1] & 0xffff0000u)}; }
; __device__ __forceinline__ void scan_wkv_sample(PP P, int l, const Ids I) {
;     ...
;         f32x4 S = *(const f32x4*)(sin_ + so);
;         f32x4 r_[4], w_[4], k_[4], a_[4], b_[4]; float v_[4];
; #pragma unroll
;         for (int s = 0; s < 4; ++s) { const unsigned row = (unsigned)MTP + sb * 4 + s, o = row * 512u + h * 64 + kseg * 4;
;             r_[s] = unpack4(*(const u32x2*)(arr + A_R * AS + o)); w_[s] = unpack4(*(const u32x2*)(arr + A_EW * AS + o)); k_[s] = unpack4(*(const u32x2*)(arr + A_KF * AS + o));
;             a_[s] = unpack4(*(const u32x2*)(arr + A_KK * AS + o)); b_[s] = unpack4(*(const u32x2*)(arr + A_BB * AS + o)); v_[s] = bf2f(arr[A_V * AS + row * 512u + h * 64 + vrow]); }
; #pragma unroll
;         for (int s = 0; s < 4; ++s) { const unsigned row = (unsigned)MTP + sb * 4 + s;
;             const float p = (S[0] * a_[s][0] + S[1] * a_[s][1]) + (S[2] * a_[s][2] + S[3] * a_[s][3]); const float sa = -row16_allsum(p);
; #pragma unroll
;             for (int j = 0; j < 4; ++j) S[j] = fmaf(S[j], __expf(-w_[s][j]), fmaf(sa, b_[s][j], v_[s] * k_[s][j]));
;             const float y = row16_allsum((S[0] * r_[s][0] + S[1] * r_[s][1]) + (S[2] * r_[s][2] + S[3] * r_[s][3]));
;             if (kseg == 0) ymix[row * 1024u + 512u + h * 64 + vrow] = f2bf(y); }
	v_lshlrev_b32_e32 v160, 16, v124
	v_and_b32_e32 v161, 0xffff0000, v124
	v_lshlrev_b32_e32 v162, 16, v125
	v_and_b32_e32 v163, 0xffff0000, v125
	v_lshlrev_b32_e32 v188, 16, v126
	v_and_b32_e32 v189, 0xffff0000, v126
	v_lshlrev_b32_e32 v190, 16, v127
	v_and_b32_e32 v191, 0xffff0000, v127
	v_lshlrev_b32_e32 v208, 16, v128
	v_and_b32_e32 v209, 0xffff0000, v128
	v_lshlrev_b32_e32 v210, 16, v129
	v_and_b32_e32 v211, 0xffff0000, v129
	v_lshlrev_b32_e32 v228, 16, v130
	v_and_b32_e32 v229, 0xffff0000, v130
	v_lshlrev_b32_e32 v230, 16, v131
	v_and_b32_e32 v231, 0xffff0000, v131
	s_waitcnt vmcnt(8)
	v_lshlrev_b32_e32 v164, 16, v132
	v_and_b32_e32 v165, 0xffff0000, v132
	v_lshlrev_b32_e32 v166, 16, v133
	v_and_b32_e32 v167, 0xffff0000, v133
	v_lshlrev_b32_e32 v192, 16, v134
	v_and_b32_e32 v193, 0xffff0000, v134
	v_lshlrev_b32_e32 v194, 16, v135
	v_and_b32_e32 v195, 0xffff0000, v135
	v_lshlrev_b32_e32 v212, 16, v136
	v_and_b32_e32 v213, 0xffff0000, v136
	v_lshlrev_b32_e32 v214, 16, v137
	v_and_b32_e32 v215, 0xffff0000, v137
	v_lshlrev_b32_e32 v232, 16, v138
	v_and_b32_e32 v233, 0xffff0000, v138
	v_lshlrev_b32_e32 v234, 16, v139
	v_and_b32_e32 v235, 0xffff0000, v139
	s_waitcnt vmcnt(4)
	v_lshlrev_b32_e32 v168, 16, v140
	v_and_b32_e32 v169, 0xffff0000, v140
	v_lshlrev_b32_e32 v170, 16, v141
	v_and_b32_e32 v171, 0xffff0000, v141
	v_lshlrev_b32_e32 v196, 16, v142
	v_and_b32_e32 v197, 0xffff0000, v142
	v_lshlrev_b32_e32 v198, 16, v143
	v_and_b32_e32 v199, 0xffff0000, v143
	v_lshlrev_b32_e32 v216, 16, v246
	v_and_b32_e32 v217, 0xffff0000, v246
	v_lshlrev_b32_e32 v218, 16, v247
	v_and_b32_e32 v219, 0xffff0000, v247
	v_lshlrev_b32_e32 v242, 16, v248
	v_and_b32_e32 v243, 0xffff0000, v248
	v_lshlrev_b32_e32 v244, 16, v249
	v_and_b32_e32 v245, 0xffff0000, v249
	s_nop 1
	global_load_dwordx4 v[108:111], v[0:1], off offset:2048
	global_load_ushort v132, v[4:5], off offset:16
	global_load_dwordx4 v[112:115], v[0:1], off offset:3072
	global_load_ushort v133, v[4:5], off offset:24
	global_load_dwordx4 v[116:119], v[50:51], off
	global_load_ushort v134, v[4:5], off offset:32
	global_load_dwordx4 v[120:123], v[50:51], off offset:1024
	global_load_ushort v135, v[4:5], off offset:40
	global_load_dwordx4 v[124:127], v[50:51], off offset:2048
	global_load_ushort v136, v[4:5], off offset:48
	global_load_dwordx4 v[128:131], v[50:51], off offset:3072
	global_load_ushort v137, v[4:5], off offset:56
	s_waitcnt vmcnt(14)
	v_lshlrev_b32_e32 v32, 16, v16
	s_nop 1
	v_mov_b32_dpp v24, v32 quad_perm:[0,0,0,0] row_mask:0xf bank_mask:0xf
	v_mov_b32_dpp v26, v32 quad_perm:[1,1,1,1] row_mask:0xf bank_mask:0xf
	v_mov_b32_dpp v28, v32 quad_perm:[2,2,2,2] row_mask:0xf bank_mask:0xf
	v_mov_b32_dpp v30, v32 quad_perm:[3,3,3,3] row_mask:0xf bank_mask:0xf
	v_pk_mul_f32 v[36:37], v[12:13], v[164:165]
	v_pk_mul_f32 v[38:39], v[24:25], v[160:161] op_sel_hi:[0,1]
	v_pk_fma_f32 v[36:37], v[14:15], v[166:167], v[36:37]
	v_pk_mul_f32 v[40:41], v[24:25], v[162:163] op_sel_hi:[0,1]
	v_add_f32_e32 v36, v36, v37
	s_nop 1
	v_add_f32_dpp v36, v36, v36 quad_perm:[1,0,3,2] row_mask:0xf bank_mask:0xf bound_ctrl:1
	s_nop 1
	v_add_f32_dpp v36, v36, v36 quad_perm:[2,3,0,1] row_mask:0xf bank_mask:0xf bound_ctrl:1
	s_nop 1
	v_add_f32_dpp v36, v36, v36 row_half_mirror row_mask:0xf bank_mask:0xf bound_ctrl:1
	s_nop 1
	v_add_f32_dpp v36, v36, v36 row_mirror row_mask:0xf bank_mask:0xf bound_ctrl:1
	v_pk_fma_f32 v[38:39], v[36:37], v[168:169], v[38:39] op_sel_hi:[0,1,1] neg_lo:[1,0,0] neg_hi:[1,0,0]
	v_pk_fma_f32 v[40:41], v[36:37], v[170:171], v[40:41] op_sel_hi:[0,1,1] neg_lo:[1,0,0] neg_hi:[1,0,0]
	v_pk_fma_f32 v[12:13], v[12:13], v[156:157], v[38:39]
	v_pk_fma_f32 v[14:15], v[14:15], v[158:159], v[40:41]
	v_pk_mul_f32 v[36:37], v[12:13], v[192:193]
	v_pk_mul_f32 v[42:43], v[12:13], v[152:153]
	v_pk_mul_f32 v[38:39], v[26:27], v[188:189] op_sel_hi:[0,1]
	v_pk_fma_f32 v[42:43], v[14:15], v[154:155], v[42:43]
	v_pk_fma_f32 v[36:37], v[14:15], v[194:195], v[36:37]
	v_add_f32_e32 v44, v42, v43
	v_pk_mul_f32 v[40:41], v[26:27], v[190:191] op_sel_hi:[0,1]
	v_add_f32_e32 v36, v36, v37
	v_add_f32_dpp v44, v44, v44 quad_perm:[1,0,3,2] row_mask:0xf bank_mask:0xf bound_ctrl:1
	s_nop 0
	v_add_f32_dpp v36, v36, v36 quad_perm:[1,0,3,2] row_mask:0xf bank_mask:0xf bound_ctrl:1
	v_add_f32_dpp v44, v44, v44 quad_perm:[2,3,0,1] row_mask:0xf bank_mask:0xf bound_ctrl:1
	s_nop 0
	v_add_f32_dpp v36, v36, v36 quad_perm:[2,3,0,1] row_mask:0xf bank_mask:0xf bound_ctrl:1
	v_add_f32_dpp v44, v44, v44 row_half_mirror row_mask:0xf bank_mask:0xf bound_ctrl:1
	s_nop 0
	v_add_f32_dpp v36, v36, v36 row_half_mirror row_mask:0xf bank_mask:0xf bound_ctrl:1
	v_add_f32_dpp v44, v44, v44 row_mirror row_mask:0xf bank_mask:0xf bound_ctrl:1
	s_nop 0
	v_add_f32_dpp v36, v36, v36 row_mirror row_mask:0xf bank_mask:0xf bound_ctrl:1
	v_pk_fma_f32 v[38:39], v[36:37], v[196:197], v[38:39] op_sel_hi:[0,1,1] neg_lo:[1,0,0] neg_hi:[1,0,0]
	v_pk_fma_f32 v[40:41], v[36:37], v[198:199], v[40:41] op_sel_hi:[0,1,1] neg_lo:[1,0,0] neg_hi:[1,0,0]
	v_pk_fma_f32 v[12:13], v[12:13], v[180:181], v[38:39]
	v_pk_fma_f32 v[14:15], v[14:15], v[182:183], v[40:41]
	v_pk_mul_f32 v[36:37], v[12:13], v[212:213]
	v_pk_mul_f32 v[42:43], v[12:13], v[176:177]
	v_pk_mul_f32 v[38:39], v[28:29], v[208:209] op_sel_hi:[0,1]
	v_pk_fma_f32 v[42:43], v[14:15], v[178:179], v[42:43]
	v_pk_fma_f32 v[36:37], v[14:15], v[214:215], v[36:37]
	v_add_f32_e32 v45, v42, v43
	v_pk_mul_f32 v[40:41], v[28:29], v[210:211] op_sel_hi:[0,1]
	v_add_f32_e32 v36, v36, v37
	v_add_f32_dpp v45, v45, v45 quad_perm:[1,0,3,2] row_mask:0xf bank_mask:0xf bound_ctrl:1
	s_nop 0
	v_add_f32_dpp v36, v36, v36 quad_perm:[1,0,3,2] row_mask:0xf bank_mask:0xf bound_ctrl:1
; __device__ __forceinline__ bf16_t f2bf(float f) { return (bf16_t)(cvt_pk_bf16(f, 0.f) & 0xffffu); }
; __device__ __forceinline__ void scan_wkv_sample(PP P, int l, const Ids I) {
;     ...
; #pragma unroll
;         for (int s = 0; s < 4; ++s) { const unsigned row = (unsigned)MTP + sb * 4 + s;
;             const float p = (S[0] * a_[s][0] + S[1] * a_[s][1]) + (S[2] * a_[s][2] + S[3] * a_[s][3]); const float sa = -row16_allsum(p);
; #pragma unroll
;             for (int j = 0; j < 4; ++j) S[j] = fmaf(S[j], __expf(-w_[s][j]), fmaf(sa, b_[s][j], v_[s] * k_[s][j]));
;             const float y = row16_allsum((S[0] * r_[s][0] + S[1] * r_[s][1]) + (S[2] * r_[s][2] + S[3] * r_[s][3]));
;             if (kseg == 0) ymix[row * 1024u + 512u + h * 64 + vrow] = f2bf(y); }
;         *(f32x4*)(out + O_SWKV + so) = S;
	v_add_f32_dpp v45, v45, v45 quad_perm:[2,3,0,1] row_mask:0xf bank_mask:0xf bound_ctrl:1
	s_nop 0
	v_add_f32_dpp v36, v36, v36 quad_perm:[2,3,0,1] row_mask:0xf bank_mask:0xf bound_ctrl:1
	v_add_f32_dpp v45, v45, v45 row_half_mirror row_mask:0xf bank_mask:0xf bound_ctrl:1
	s_nop 0
	v_add_f32_dpp v36, v36, v36 row_half_mirror row_mask:0xf bank_mask:0xf bound_ctrl:1
	v_add_f32_dpp v45, v45, v45 row_mirror row_mask:0xf bank_mask:0xf bound_ctrl:1
	s_nop 0
	v_add_f32_dpp v36, v36, v36 row_mirror row_mask:0xf bank_mask:0xf bound_ctrl:1
	v_pk_fma_f32 v[38:39], v[36:37], v[216:217], v[38:39] op_sel_hi:[0,1,1] neg_lo:[1,0,0] neg_hi:[1,0,0]
	v_pk_fma_f32 v[40:41], v[36:37], v[218:219], v[40:41] op_sel_hi:[0,1,1] neg_lo:[1,0,0] neg_hi:[1,0,0]
	v_pk_fma_f32 v[12:13], v[12:13], v[204:205], v[38:39]
	v_pk_fma_f32 v[14:15], v[14:15], v[206:207], v[40:41]
	v_pk_mul_f32 v[36:37], v[12:13], v[232:233]
	v_pk_mul_f32 v[42:43], v[12:13], v[200:201]
	v_pk_mul_f32 v[38:39], v[30:31], v[228:229] op_sel_hi:[0,1]
	v_pk_fma_f32 v[42:43], v[14:15], v[202:203], v[42:43]
	v_pk_fma_f32 v[36:37], v[14:15], v[234:235], v[36:37]
	v_add_f32_e32 v46, v42, v43
	v_pk_mul_f32 v[40:41], v[30:31], v[230:231] op_sel_hi:[0,1]
	v_add_f32_e32 v36, v36, v37
	v_add_f32_dpp v46, v46, v46 quad_perm:[1,0,3,2] row_mask:0xf bank_mask:0xf bound_ctrl:1
	s_nop 0
	v_add_f32_dpp v36, v36, v36 quad_perm:[1,0,3,2] row_mask:0xf bank_mask:0xf bound_ctrl:1
	v_add_f32_dpp v46, v46, v46 quad_perm:[2,3,0,1] row_mask:0xf bank_mask:0xf bound_ctrl:1
	s_nop 0
	v_add_f32_dpp v36, v36, v36 quad_perm:[2,3,0,1] row_mask:0xf bank_mask:0xf bound_ctrl:1
	v_add_f32_dpp v46, v46, v46 row_half_mirror row_mask:0xf bank_mask:0xf bound_ctrl:1
	s_nop 0
	v_add_f32_dpp v36, v36, v36 row_half_mirror row_mask:0xf bank_mask:0xf bound_ctrl:1
	v_add_f32_dpp v46, v46, v46 row_mirror row_mask:0xf bank_mask:0xf bound_ctrl:1
	s_nop 0
	v_add_f32_dpp v36, v36, v36 row_mirror row_mask:0xf bank_mask:0xf bound_ctrl:1
	v_pk_fma_f32 v[38:39], v[36:37], v[242:243], v[38:39] op_sel_hi:[0,1,1] neg_lo:[1,0,0] neg_hi:[1,0,0]
	v_pk_fma_f32 v[40:41], v[36:37], v[244:245], v[40:41] op_sel_hi:[0,1,1] neg_lo:[1,0,0] neg_hi:[1,0,0]
	v_pk_fma_f32 v[12:13], v[12:13], v[224:225], v[38:39]
	v_pk_fma_f32 v[14:15], v[14:15], v[226:227], v[40:41]
	global_store_dwordx4 v[2:3], v[12:15], off
	v_pk_mul_f32 v[42:43], v[12:13], v[220:221]
	v_pk_fma_f32 v[42:43], v[14:15], v[222:223], v[42:43]
	v_add_f32_e32 v47, v42, v43
	s_nop 1
	v_add_f32_dpp v47, v47, v47 quad_perm:[1,0,3,2] row_mask:0xf bank_mask:0xf bound_ctrl:1
	s_nop 1
	v_add_f32_dpp v47, v47, v47 quad_perm:[2,3,0,1] row_mask:0xf bank_mask:0xf bound_ctrl:1
	s_nop 1
	v_add_f32_dpp v47, v47, v47 row_half_mirror row_mask:0xf bank_mask:0xf bound_ctrl:1
	s_nop 1
	v_add_f32_dpp v47, v47, v47 row_mirror row_mask:0xf bank_mask:0xf bound_ctrl:1
	v_cndmask_b32_e64 v48, v44, v45, s[8:9]
	v_cndmask_b32_e64 v48, v48, v46, s[12:13]
	s_nop 1
	v_cndmask_b32_e64 v48, v48, v47, s[14:15]
	s_and_saveexec_b64 s[6:7], s[18:19]
	ds_write_b32 v17, v48
	s_mov_b64 exec, s[6:7]
	s_waitcnt vmcnt(13)
	v_lshlrev_b32_e32 v32, 16, v58
	s_nop 1
	v_mov_b32_dpp v24, v32 quad_perm:[0,0,0,0] row_mask:0xf bank_mask:0xf
	v_mov_b32_dpp v26, v32 quad_perm:[1,1,1,1] row_mask:0xf bank_mask:0xf
	v_mov_b32_dpp v28, v32 quad_perm:[2,2,2,2] row_mask:0xf bank_mask:0xf
	v_mov_b32_dpp v30, v32 quad_perm:[3,3,3,3] row_mask:0xf bank_mask:0xf
	v_pk_mul_f32 v[36:37], v[54:55], v[164:165]
	v_pk_mul_f32 v[38:39], v[24:25], v[160:161] op_sel_hi:[0,1]
	v_pk_fma_f32 v[36:37], v[56:57], v[166:167], v[36:37]
	v_pk_mul_f32 v[40:41], v[24:25], v[162:163] op_sel_hi:[0,1]
	v_add_f32_e32 v36, v36, v37
	s_nop 1
	v_add_f32_dpp v36, v36, v36 quad_perm:[1,0,3,2] row_mask:0xf bank_mask:0xf bound_ctrl:1
	s_nop 1
	v_add_f32_dpp v36, v36, v36 quad_perm:[2,3,0,1] row_mask:0xf bank_mask:0xf bound_ctrl:1
	s_nop 1
	v_add_f32_dpp v36, v36, v36 row_half_mirror row_mask:0xf bank_mask:0xf bound_ctrl:1
	s_nop 1
	v_add_f32_dpp v36, v36, v36 row_mirror row_mask:0xf bank_mask:0xf bound_ctrl:1
	v_pk_fma_f32 v[38:39], v[36:37], v[168:169], v[38:39] op_sel_hi:[0,1,1] neg_lo:[1,0,0] neg_hi:[1,0,0]
	v_pk_fma_f32 v[40:41], v[36:37], v[170:171], v[40:41] op_sel_hi:[0,1,1] neg_lo:[1,0,0] neg_hi:[1,0,0]
	v_pk_fma_f32 v[54:55], v[54:55], v[156:157], v[38:39]
	v_pk_fma_f32 v[56:57], v[56:57], v[158:159], v[40:41]
	v_pk_mul_f32 v[36:37], v[54:55], v[192:193]
	v_pk_mul_f32 v[42:43], v[54:55], v[152:153]
	v_pk_mul_f32 v[38:39], v[26:27], v[188:189] op_sel_hi:[0,1]
	v_pk_fma_f32 v[42:43], v[56:57], v[154:155], v[42:43]
	v_pk_fma_f32 v[36:37], v[56:57], v[194:195], v[36:37]
	v_add_f32_e32 v44, v42, v43
	v_pk_mul_f32 v[40:41], v[26:27], v[190:191] op_sel_hi:[0,1]
	v_add_f32_e32 v36, v36, v37
	v_add_f32_dpp v44, v44, v44 quad_perm:[1,0,3,2] row_mask:0xf bank_mask:0xf bound_ctrl:1
	s_nop 0
	v_add_f32_dpp v36, v36, v36 quad_perm:[1,0,3,2] row_mask:0xf bank_mask:0xf bound_ctrl:1
	v_add_f32_dpp v44, v44, v44 quad_perm:[2,3,0,1] row_mask:0xf bank_mask:0xf bound_ctrl:1
	s_nop 0
	v_add_f32_dpp v36, v36, v36 quad_perm:[2,3,0,1] row_mask:0xf bank_mask:0xf bound_ctrl:1
	v_add_f32_dpp v44, v44, v44 row_half_mirror row_mask:0xf bank_mask:0xf bound_ctrl:1
	s_nop 0
	v_add_f32_dpp v36, v36, v36 row_half_mirror row_mask:0xf bank_mask:0xf bound_ctrl:1
	v_add_f32_dpp v44, v44, v44 row_mirror row_mask:0xf bank_mask:0xf bound_ctrl:1
	s_nop 0
	v_add_f32_dpp v36, v36, v36 row_mirror row_mask:0xf bank_mask:0xf bound_ctrl:1
	v_pk_fma_f32 v[38:39], v[36:37], v[196:197], v[38:39] op_sel_hi:[0,1,1] neg_lo:[1,0,0] neg_hi:[1,0,0]
	v_pk_fma_f32 v[40:41], v[36:37], v[198:199], v[40:41] op_sel_hi:[0,1,1] neg_lo:[1,0,0] neg_hi:[1,0,0]
; __device__ __forceinline__ bf16_t f2bf(float f) { return (bf16_t)(cvt_pk_bf16(f, 0.f) & 0xffffu); }
; __device__ __forceinline__ void scan_wkv_sample(PP P, int l, const Ids I) {
;     ...
; #pragma unroll
;         for (int s = 0; s < 4; ++s) { const unsigned row = (unsigned)MTP + sb * 4 + s;
;             const float p = (S[0] * a_[s][0] + S[1] * a_[s][1]) + (S[2] * a_[s][2] + S[3] * a_[s][3]); const float sa = -row16_allsum(p);
; #pragma unroll
;             for (int j = 0; j < 4; ++j) S[j] = fmaf(S[j], __expf(-w_[s][j]), fmaf(sa, b_[s][j], v_[s] * k_[s][j]));
;             const float y = row16_allsum((S[0] * r_[s][0] + S[1] * r_[s][1]) + (S[2] * r_[s][2] + S[3] * r_[s][3]));
;             if (kseg == 0) ymix[row * 1024u + 512u + h * 64 + vrow] = f2bf(y); }
;         *(f32x4*)(out + O_SWKV + so) = S;
	v_pk_fma_f32 v[54:55], v[54:55], v[180:181], v[38:39]
	v_pk_fma_f32 v[56:57], v[56:57], v[182:183], v[40:41]
	v_pk_mul_f32 v[36:37], v[54:55], v[212:213]
	v_pk_mul_f32 v[42:43], v[54:55], v[176:177]
	v_pk_mul_f32 v[38:39], v[28:29], v[208:209] op_sel_hi:[0,1]
	v_pk_fma_f32 v[42:43], v[56:57], v[178:179], v[42:43]
	v_pk_fma_f32 v[36:37], v[56:57], v[214:215], v[36:37]
	v_add_f32_e32 v45, v42, v43
	v_pk_mul_f32 v[40:41], v[28:29], v[210:211] op_sel_hi:[0,1]
	v_add_f32_e32 v36, v36, v37
	v_add_f32_dpp v45, v45, v45 quad_perm:[1,0,3,2] row_mask:0xf bank_mask:0xf bound_ctrl:1
	s_nop 0
	v_add_f32_dpp v36, v36, v36 quad_perm:[1,0,3,2] row_mask:0xf bank_mask:0xf bound_ctrl:1
	v_add_f32_dpp v45, v45, v45 quad_perm:[2,3,0,1] row_mask:0xf bank_mask:0xf bound_ctrl:1
	s_nop 0
	v_add_f32_dpp v36, v36, v36 quad_perm:[2,3,0,1] row_mask:0xf bank_mask:0xf bound_ctrl:1
	v_add_f32_dpp v45, v45, v45 row_half_mirror row_mask:0xf bank_mask:0xf bound_ctrl:1
	s_nop 0
	v_add_f32_dpp v36, v36, v36 row_half_mirror row_mask:0xf bank_mask:0xf bound_ctrl:1
	v_add_f32_dpp v45, v45, v45 row_mirror row_mask:0xf bank_mask:0xf bound_ctrl:1
	s_nop 0
	v_add_f32_dpp v36, v36, v36 row_mirror row_mask:0xf bank_mask:0xf bound_ctrl:1
	v_pk_fma_f32 v[38:39], v[36:37], v[216:217], v[38:39] op_sel_hi:[0,1,1] neg_lo:[1,0,0] neg_hi:[1,0,0]
	v_pk_fma_f32 v[40:41], v[36:37], v[218:219], v[40:41] op_sel_hi:[0,1,1] neg_lo:[1,0,0] neg_hi:[1,0,0]
	v_pk_fma_f32 v[54:55], v[54:55], v[204:205], v[38:39]
	v_pk_fma_f32 v[56:57], v[56:57], v[206:207], v[40:41]
	v_pk_mul_f32 v[36:37], v[54:55], v[232:233]
	v_pk_mul_f32 v[42:43], v[54:55], v[200:201]
	v_pk_mul_f32 v[38:39], v[30:31], v[228:229] op_sel_hi:[0,1]
	v_pk_fma_f32 v[42:43], v[56:57], v[202:203], v[42:43]
	v_pk_fma_f32 v[36:37], v[56:57], v[234:235], v[36:37]
	v_add_f32_e32 v46, v42, v43
	v_pk_mul_f32 v[40:41], v[30:31], v[230:231] op_sel_hi:[0,1]
	v_add_f32_e32 v36, v36, v37
	v_add_f32_dpp v46, v46, v46 quad_perm:[1,0,3,2] row_mask:0xf bank_mask:0xf bound_ctrl:1
	s_nop 0
	v_add_f32_dpp v36, v36, v36 quad_perm:[1,0,3,2] row_mask:0xf bank_mask:0xf bound_ctrl:1
	v_add_f32_dpp v46, v46, v46 quad_perm:[2,3,0,1] row_mask:0xf bank_mask:0xf bound_ctrl:1
	s_nop 0
	v_add_f32_dpp v36, v36, v36 quad_perm:[2,3,0,1] row_mask:0xf bank_mask:0xf bound_ctrl:1
	v_add_f32_dpp v46, v46, v46 row_half_mirror row_mask:0xf bank_mask:0xf bound_ctrl:1
	s_nop 0
	v_add_f32_dpp v36, v36, v36 row_half_mirror row_mask:0xf bank_mask:0xf bound_ctrl:1
	v_add_f32_dpp v46, v46, v46 row_mirror row_mask:0xf bank_mask:0xf bound_ctrl:1
	s_nop 0
	v_add_f32_dpp v36, v36, v36 row_mirror row_mask:0xf bank_mask:0xf bound_ctrl:1
	v_pk_fma_f32 v[38:39], v[36:37], v[242:243], v[38:39] op_sel_hi:[0,1,1] neg_lo:[1,0,0] neg_hi:[1,0,0]
	v_pk_fma_f32 v[40:41], v[36:37], v[244:245], v[40:41] op_sel_hi:[0,1,1] neg_lo:[1,0,0] neg_hi:[1,0,0]
	v_pk_fma_f32 v[54:55], v[54:55], v[224:225], v[38:39]
	v_pk_fma_f32 v[56:57], v[56:57], v[226:227], v[40:41]
	global_store_dwordx4 v[2:3], v[54:57], off offset:1024
	v_pk_mul_f32 v[42:43], v[54:55], v[220:221]
	v_pk_fma_f32 v[42:43], v[56:57], v[222:223], v[42:43]
	v_add_f32_e32 v47, v42, v43
	s_nop 1
	v_add_f32_dpp v47, v47, v47 quad_perm:[1,0,3,2] row_mask:0xf bank_mask:0xf bound_ctrl:1
	s_nop 1
	v_add_f32_dpp v47, v47, v47 quad_perm:[2,3,0,1] row_mask:0xf bank_mask:0xf bound_ctrl:1
	s_nop 1
	v_add_f32_dpp v47, v47, v47 row_half_mirror row_mask:0xf bank_mask:0xf bound_ctrl:1
	s_nop 1
	v_add_f32_dpp v47, v47, v47 row_mirror row_mask:0xf bank_mask:0xf bound_ctrl:1
	v_cndmask_b32_e64 v48, v44, v45, s[8:9]
	v_cndmask_b32_e64 v48, v48, v46, s[12:13]
	s_nop 1
	v_cndmask_b32_e64 v48, v48, v47, s[14:15]
	s_and_saveexec_b64 s[6:7], s[18:19]
	ds_write_b32 v17, v48 offset:16
	s_mov_b64 exec, s[6:7]
	s_waitcnt vmcnt(12)
	v_lshlrev_b32_e32 v32, 16, v132
	s_nop 1
	v_mov_b32_dpp v24, v32 quad_perm:[0,0,0,0] row_mask:0xf bank_mask:0xf
	v_mov_b32_dpp v26, v32 quad_perm:[1,1,1,1] row_mask:0xf bank_mask:0xf
	v_mov_b32_dpp v28, v32 quad_perm:[2,2,2,2] row_mask:0xf bank_mask:0xf
	v_mov_b32_dpp v30, v32 quad_perm:[3,3,3,3] row_mask:0xf bank_mask:0xf
	v_pk_mul_f32 v[36:37], v[108:109], v[164:165]
	v_pk_mul_f32 v[38:39], v[24:25], v[160:161] op_sel_hi:[0,1]
	v_pk_fma_f32 v[36:37], v[110:111], v[166:167], v[36:37]
	v_pk_mul_f32 v[40:41], v[24:25], v[162:163] op_sel_hi:[0,1]
	v_add_f32_e32 v36, v36, v37
	s_nop 1
	v_add_f32_dpp v36, v36, v36 quad_perm:[1,0,3,2] row_mask:0xf bank_mask:0xf bound_ctrl:1
	s_nop 1
	v_add_f32_dpp v36, v36, v36 quad_perm:[2,3,0,1] row_mask:0xf bank_mask:0xf bound_ctrl:1
	s_nop 1
	v_add_f32_dpp v36, v36, v36 row_half_mirror row_mask:0xf bank_mask:0xf bound_ctrl:1
	s_nop 1
	v_add_f32_dpp v36, v36, v36 row_mirror row_mask:0xf bank_mask:0xf bound_ctrl:1
	v_pk_fma_f32 v[38:39], v[36:37], v[168:169], v[38:39] op_sel_hi:[0,1,1] neg_lo:[1,0,0] neg_hi:[1,0,0]
	v_pk_fma_f32 v[40:41], v[36:37], v[170:171], v[40:41] op_sel_hi:[0,1,1] neg_lo:[1,0,0] neg_hi:[1,0,0]
	v_pk_fma_f32 v[108:109], v[108:109], v[156:157], v[38:39]
	v_pk_fma_f32 v[110:111], v[110:111], v[158:159], v[40:41]
	v_pk_mul_f32 v[36:37], v[108:109], v[192:193]
	v_pk_mul_f32 v[42:43], v[108:109], v[152:153]
	v_pk_mul_f32 v[38:39], v[26:27], v[188:189] op_sel_hi:[0,1]
	v_pk_fma_f32 v[42:43], v[110:111], v[154:155], v[42:43]
	v_pk_fma_f32 v[36:37], v[110:111], v[194:195], v[36:37]
	v_add_f32_e32 v44, v42, v43
	v_pk_mul_f32 v[40:41], v[26:27], v[190:191] op_sel_hi:[0,1]
	v_add_f32_e32 v36, v36, v37
	v_add_f32_dpp v44, v44, v44 quad_perm:[1,0,3,2] row_mask:0xf bank_mask:0xf bound_ctrl:1
	s_nop 0
	v_add_f32_dpp v36, v36, v36 quad_perm:[1,0,3,2] row_mask:0xf bank_mask:0xf bound_ctrl:1
; __device__ __forceinline__ bf16_t f2bf(float f) { return (bf16_t)(cvt_pk_bf16(f, 0.f) & 0xffffu); }
; __device__ __forceinline__ void scan_wkv_sample(PP P, int l, const Ids I) {
;     ...
; #pragma unroll
;         for (int s = 0; s < 4; ++s) { const unsigned row = (unsigned)MTP + sb * 4 + s;
;             const float p = (S[0] * a_[s][0] + S[1] * a_[s][1]) + (S[2] * a_[s][2] + S[3] * a_[s][3]); const float sa = -row16_allsum(p);
; #pragma unroll
;             for (int j = 0; j < 4; ++j) S[j] = fmaf(S[j], __expf(-w_[s][j]), fmaf(sa, b_[s][j], v_[s] * k_[s][j]));
;             const float y = row16_allsum((S[0] * r_[s][0] + S[1] * r_[s][1]) + (S[2] * r_[s][2] + S[3] * r_[s][3]));
;             if (kseg == 0) ymix[row * 1024u + 512u + h * 64 + vrow] = f2bf(y); }
;         *(f32x4*)(out + O_SWKV + so) = S;
	v_add_f32_dpp v44, v44, v44 quad_perm:[2,3,0,1] row_mask:0xf bank_mask:0xf bound_ctrl:1
	s_nop 0
	v_add_f32_dpp v36, v36, v36 quad_perm:[2,3,0,1] row_mask:0xf bank_mask:0xf bound_ctrl:1
	v_add_f32_dpp v44, v44, v44 row_half_mirror row_mask:0xf bank_mask:0xf bound_ctrl:1
	s_nop 0
	v_add_f32_dpp v36, v36, v36 row_half_mirror row_mask:0xf bank_mask:0xf bound_ctrl:1
	v_add_f32_dpp v44, v44, v44 row_mirror row_mask:0xf bank_mask:0xf bound_ctrl:1
	s_nop 0
	v_add_f32_dpp v36, v36, v36 row_mirror row_mask:0xf bank_mask:0xf bound_ctrl:1
	v_pk_fma_f32 v[38:39], v[36:37], v[196:197], v[38:39] op_sel_hi:[0,1,1] neg_lo:[1,0,0] neg_hi:[1,0,0]
	v_pk_fma_f32 v[40:41], v[36:37], v[198:199], v[40:41] op_sel_hi:[0,1,1] neg_lo:[1,0,0] neg_hi:[1,0,0]
	v_pk_fma_f32 v[108:109], v[108:109], v[180:181], v[38:39]
	v_pk_fma_f32 v[110:111], v[110:111], v[182:183], v[40:41]
	v_pk_mul_f32 v[36:37], v[108:109], v[212:213]
	v_pk_mul_f32 v[42:43], v[108:109], v[176:177]
	v_pk_mul_f32 v[38:39], v[28:29], v[208:209] op_sel_hi:[0,1]
	v_pk_fma_f32 v[42:43], v[110:111], v[178:179], v[42:43]
	v_pk_fma_f32 v[36:37], v[110:111], v[214:215], v[36:37]
	v_add_f32_e32 v45, v42, v43
	v_pk_mul_f32 v[40:41], v[28:29], v[210:211] op_sel_hi:[0,1]
	v_add_f32_e32 v36, v36, v37
	v_add_f32_dpp v45, v45, v45 quad_perm:[1,0,3,2] row_mask:0xf bank_mask:0xf bound_ctrl:1
	s_nop 0
	v_add_f32_dpp v36, v36, v36 quad_perm:[1,0,3,2] row_mask:0xf bank_mask:0xf bound_ctrl:1
	v_add_f32_dpp v45, v45, v45 quad_perm:[2,3,0,1] row_mask:0xf bank_mask:0xf bound_ctrl:1
	s_nop 0
	v_add_f32_dpp v36, v36, v36 quad_perm:[2,3,0,1] row_mask:0xf bank_mask:0xf bound_ctrl:1
	v_add_f32_dpp v45, v45, v45 row_half_mirror row_mask:0xf bank_mask:0xf bound_ctrl:1
	s_nop 0
	v_add_f32_dpp v36, v36, v36 row_half_mirror row_mask:0xf bank_mask:0xf bound_ctrl:1
	v_add_f32_dpp v45, v45, v45 row_mirror row_mask:0xf bank_mask:0xf bound_ctrl:1
	s_nop 0
	v_add_f32_dpp v36, v36, v36 row_mirror row_mask:0xf bank_mask:0xf bound_ctrl:1
	v_pk_fma_f32 v[38:39], v[36:37], v[216:217], v[38:39] op_sel_hi:[0,1,1] neg_lo:[1,0,0] neg_hi:[1,0,0]
	v_pk_fma_f32 v[40:41], v[36:37], v[218:219], v[40:41] op_sel_hi:[0,1,1] neg_lo:[1,0,0] neg_hi:[1,0,0]
	v_pk_fma_f32 v[108:109], v[108:109], v[204:205], v[38:39]
	v_pk_fma_f32 v[110:111], v[110:111], v[206:207], v[40:41]
	v_pk_mul_f32 v[36:37], v[108:109], v[232:233]
	v_pk_mul_f32 v[42:43], v[108:109], v[200:201]
	v_pk_mul_f32 v[38:39], v[30:31], v[228:229] op_sel_hi:[0,1]
	v_pk_fma_f32 v[42:43], v[110:111], v[202:203], v[42:43]
	v_pk_fma_f32 v[36:37], v[110:111], v[234:235], v[36:37]
	v_add_f32_e32 v46, v42, v43
	v_pk_mul_f32 v[40:41], v[30:31], v[230:231] op_sel_hi:[0,1]
	v_add_f32_e32 v36, v36, v37
	v_add_f32_dpp v46, v46, v46 quad_perm:[1,0,3,2] row_mask:0xf bank_mask:0xf bound_ctrl:1
	s_nop 0
	v_add_f32_dpp v36, v36, v36 quad_perm:[1,0,3,2] row_mask:0xf bank_mask:0xf bound_ctrl:1
	v_add_f32_dpp v46, v46, v46 quad_perm:[2,3,0,1] row_mask:0xf bank_mask:0xf bound_ctrl:1
	s_nop 0
	v_add_f32_dpp v36, v36, v36 quad_perm:[2,3,0,1] row_mask:0xf bank_mask:0xf bound_ctrl:1
	v_add_f32_dpp v46, v46, v46 row_half_mirror row_mask:0xf bank_mask:0xf bound_ctrl:1
	s_nop 0
	v_add_f32_dpp v36, v36, v36 row_half_mirror row_mask:0xf bank_mask:0xf bound_ctrl:1
	v_add_f32_dpp v46, v46, v46 row_mirror row_mask:0xf bank_mask:0xf bound_ctrl:1
	s_nop 0
	v_add_f32_dpp v36, v36, v36 row_mirror row_mask:0xf bank_mask:0xf bound_ctrl:1
	v_pk_fma_f32 v[38:39], v[36:37], v[242:243], v[38:39] op_sel_hi:[0,1,1] neg_lo:[1,0,0] neg_hi:[1,0,0]
	v_pk_fma_f32 v[40:41], v[36:37], v[244:245], v[40:41] op_sel_hi:[0,1,1] neg_lo:[1,0,0] neg_hi:[1,0,0]
	v_pk_fma_f32 v[108:109], v[108:109], v[224:225], v[38:39]
	v_pk_fma_f32 v[110:111], v[110:111], v[226:227], v[40:41]
	global_store_dwordx4 v[2:3], v[108:111], off offset:2048
	v_pk_mul_f32 v[42:43], v[108:109], v[220:221]
	v_pk_fma_f32 v[42:43], v[110:111], v[222:223], v[42:43]
	v_add_f32_e32 v47, v42, v43
	s_nop 1
	v_add_f32_dpp v47, v47, v47 quad_perm:[1,0,3,2] row_mask:0xf bank_mask:0xf bound_ctrl:1
	s_nop 1
	v_add_f32_dpp v47, v47, v47 quad_perm:[2,3,0,1] row_mask:0xf bank_mask:0xf bound_ctrl:1
	s_nop 1
	v_add_f32_dpp v47, v47, v47 row_half_mirror row_mask:0xf bank_mask:0xf bound_ctrl:1
	s_nop 1
	v_add_f32_dpp v47, v47, v47 row_mirror row_mask:0xf bank_mask:0xf bound_ctrl:1
	v_cndmask_b32_e64 v48, v44, v45, s[8:9]
	v_cndmask_b32_e64 v48, v48, v46, s[12:13]
	s_nop 1
	v_cndmask_b32_e64 v48, v48, v47, s[14:15]
	s_and_saveexec_b64 s[6:7], s[18:19]
	ds_write_b32 v17, v48 offset:32
	s_mov_b64 exec, s[6:7]
	s_waitcnt vmcnt(11)
; __device__ __forceinline__ bf16_t f2bf(float f) { return (bf16_t)(cvt_pk_bf16(f, 0.f) & 0xffffu); }
; __device__ __forceinline__ void scan_wkv_sample(PP P, int l, const Ids I) {
;     ...
; #pragma unroll
;         for (int s = 0; s < 4; ++s) { const unsigned row = (unsigned)MTP + sb * 4 + s;
;             const float p = (S[0] * a_[s][0] + S[1] * a_[s][1]) + (S[2] * a_[s][2] + S[3] * a_[s][3]); const float sa = -row16_allsum(p);
; #pragma unroll
;             for (int j = 0; j < 4; ++j) S[j] = fmaf(S[j], __expf(-w_[s][j]), fmaf(sa, b_[s][j], v_[s] * k_[s][j]));
;             const float y = row16_allsum((S[0] * r_[s][0] + S[1] * r_[s][1]) + (S[2] * r_[s][2] + S[3] * r_[s][3]));
;             if (kseg == 0) ymix[row * 1024u + 512u + h * 64 + vrow] = f2bf(y); }
;         *(f32x4*)(out + O_SWKV + so) = S;
	v_lshlrev_b32_e32 v32, 16, v133
	s_nop 1
	v_mov_b32_dpp v24, v32 quad_perm:[0,0,0,0] row_mask:0xf bank_mask:0xf
	v_mov_b32_dpp v26, v32 quad_perm:[1,1,1,1] row_mask:0xf bank_mask:0xf
	v_mov_b32_dpp v28, v32 quad_perm:[2,2,2,2] row_mask:0xf bank_mask:0xf
	v_mov_b32_dpp v30, v32 quad_perm:[3,3,3,3] row_mask:0xf bank_mask:0xf
	v_pk_mul_f32 v[36:37], v[112:113], v[164:165]
	v_pk_mul_f32 v[38:39], v[24:25], v[160:161] op_sel_hi:[0,1]
	v_pk_fma_f32 v[36:37], v[114:115], v[166:167], v[36:37]
	v_pk_mul_f32 v[40:41], v[24:25], v[162:163] op_sel_hi:[0,1]
	v_add_f32_e32 v36, v36, v37
	s_nop 1
	v_add_f32_dpp v36, v36, v36 quad_perm:[1,0,3,2] row_mask:0xf bank_mask:0xf bound_ctrl:1
	s_nop 1
	v_add_f32_dpp v36, v36, v36 quad_perm:[2,3,0,1] row_mask:0xf bank_mask:0xf bound_ctrl:1
	s_nop 1
	v_add_f32_dpp v36, v36, v36 row_half_mirror row_mask:0xf bank_mask:0xf bound_ctrl:1
	s_nop 1
	v_add_f32_dpp v36, v36, v36 row_mirror row_mask:0xf bank_mask:0xf bound_ctrl:1
	v_pk_fma_f32 v[38:39], v[36:37], v[168:169], v[38:39] op_sel_hi:[0,1,1] neg_lo:[1,0,0] neg_hi:[1,0,0]
	v_pk_fma_f32 v[40:41], v[36:37], v[170:171], v[40:41] op_sel_hi:[0,1,1] neg_lo:[1,0,0] neg_hi:[1,0,0]
	v_pk_fma_f32 v[112:113], v[112:113], v[156:157], v[38:39]
	v_pk_fma_f32 v[114:115], v[114:115], v[158:159], v[40:41]
	v_pk_mul_f32 v[36:37], v[112:113], v[192:193]
	v_pk_mul_f32 v[42:43], v[112:113], v[152:153]
	v_pk_mul_f32 v[38:39], v[26:27], v[188:189] op_sel_hi:[0,1]
	v_pk_fma_f32 v[42:43], v[114:115], v[154:155], v[42:43]
	v_pk_fma_f32 v[36:37], v[114:115], v[194:195], v[36:37]
	v_add_f32_e32 v44, v42, v43
	v_pk_mul_f32 v[40:41], v[26:27], v[190:191] op_sel_hi:[0,1]
	v_add_f32_e32 v36, v36, v37
	v_add_f32_dpp v44, v44, v44 quad_perm:[1,0,3,2] row_mask:0xf bank_mask:0xf bound_ctrl:1
	s_nop 0
	v_add_f32_dpp v36, v36, v36 quad_perm:[1,0,3,2] row_mask:0xf bank_mask:0xf bound_ctrl:1
	v_add_f32_dpp v44, v44, v44 quad_perm:[2,3,0,1] row_mask:0xf bank_mask:0xf bound_ctrl:1
	s_nop 0
	v_add_f32_dpp v36, v36, v36 quad_perm:[2,3,0,1] row_mask:0xf bank_mask:0xf bound_ctrl:1
	v_add_f32_dpp v44, v44, v44 row_half_mirror row_mask:0xf bank_mask:0xf bound_ctrl:1
	s_nop 0
	v_add_f32_dpp v36, v36, v36 row_half_mirror row_mask:0xf bank_mask:0xf bound_ctrl:1
	v_add_f32_dpp v44, v44, v44 row_mirror row_mask:0xf bank_mask:0xf bound_ctrl:1
	s_nop 0
	v_add_f32_dpp v36, v36, v36 row_mirror row_mask:0xf bank_mask:0xf bound_ctrl:1
	v_pk_fma_f32 v[38:39], v[36:37], v[196:197], v[38:39] op_sel_hi:[0,1,1] neg_lo:[1,0,0] neg_hi:[1,0,0]
	v_pk_fma_f32 v[40:41], v[36:37], v[198:199], v[40:41] op_sel_hi:[0,1,1] neg_lo:[1,0,0] neg_hi:[1,0,0]
	v_pk_fma_f32 v[112:113], v[112:113], v[180:181], v[38:39]
	v_pk_fma_f32 v[114:115], v[114:115], v[182:183], v[40:41]
	v_pk_mul_f32 v[36:37], v[112:113], v[212:213]
	v_pk_mul_f32 v[42:43], v[112:113], v[176:177]
	v_pk_mul_f32 v[38:39], v[28:29], v[208:209] op_sel_hi:[0,1]
	v_pk_fma_f32 v[42:43], v[114:115], v[178:179], v[42:43]
	v_pk_fma_f32 v[36:37], v[114:115], v[214:215], v[36:37]
	v_add_f32_e32 v45, v42, v43
	v_pk_mul_f32 v[40:41], v[28:29], v[210:211] op_sel_hi:[0,1]
	v_add_f32_e32 v36, v36, v37
	v_add_f32_dpp v45, v45, v45 quad_perm:[1,0,3,2] row_mask:0xf bank_mask:0xf bound_ctrl:1
	s_nop 0
	v_add_f32_dpp v36, v36, v36 quad_perm:[1,0,3,2] row_mask:0xf bank_mask:0xf bound_ctrl:1
	v_add_f32_dpp v45, v45, v45 quad_perm:[2,3,0,1] row_mask:0xf bank_mask:0xf bound_ctrl:1
	s_nop 0
	v_add_f32_dpp v36, v36, v36 quad_perm:[2,3,0,1] row_mask:0xf bank_mask:0xf bound_ctrl:1
	v_add_f32_dpp v45, v45, v45 row_half_mirror row_mask:0xf bank_mask:0xf bound_ctrl:1
	s_nop 0
	v_add_f32_dpp v36, v36, v36 row_half_mirror row_mask:0xf bank_mask:0xf bound_ctrl:1
	v_add_f32_dpp v45, v45, v45 row_mirror row_mask:0xf bank_mask:0xf bound_ctrl:1
	s_nop 0
	v_add_f32_dpp v36, v36, v36 row_mirror row_mask:0xf bank_mask:0xf bound_ctrl:1
	v_pk_fma_f32 v[38:39], v[36:37], v[216:217], v[38:39] op_sel_hi:[0,1,1] neg_lo:[1,0,0] neg_hi:[1,0,0]
	v_pk_fma_f32 v[40:41], v[36:37], v[218:219], v[40:41] op_sel_hi:[0,1,1] neg_lo:[1,0,0] neg_hi:[1,0,0]
	v_pk_fma_f32 v[112:113], v[112:113], v[204:205], v[38:39]
	v_pk_fma_f32 v[114:115], v[114:115], v[206:207], v[40:41]
	v_pk_mul_f32 v[36:37], v[112:113], v[232:233]
	v_pk_mul_f32 v[42:43], v[112:113], v[200:201]
	v_pk_mul_f32 v[38:39], v[30:31], v[228:229] op_sel_hi:[0,1]
	v_pk_fma_f32 v[42:43], v[114:115], v[202:203], v[42:43]
	v_pk_fma_f32 v[36:37], v[114:115], v[234:235], v[36:37]
	v_add_f32_e32 v46, v42, v43
	v_pk_mul_f32 v[40:41], v[30:31], v[230:231] op_sel_hi:[0,1]
	v_add_f32_e32 v36, v36, v37
	v_add_f32_dpp v46, v46, v46 quad_perm:[1,0,3,2] row_mask:0xf bank_mask:0xf bound_ctrl:1
	s_nop 0
	v_add_f32_dpp v36, v36, v36 quad_perm:[1,0,3,2] row_mask:0xf bank_mask:0xf bound_ctrl:1
	v_add_f32_dpp v46, v46, v46 quad_perm:[2,3,0,1] row_mask:0xf bank_mask:0xf bound_ctrl:1
	s_nop 0
	v_add_f32_dpp v36, v36, v36 quad_perm:[2,3,0,1] row_mask:0xf bank_mask:0xf bound_ctrl:1
	v_add_f32_dpp v46, v46, v46 row_half_mirror row_mask:0xf bank_mask:0xf bound_ctrl:1
	s_nop 0
	v_add_f32_dpp v36, v36, v36 row_half_mirror row_mask:0xf bank_mask:0xf bound_ctrl:1
	v_add_f32_dpp v46, v46, v46 row_mirror row_mask:0xf bank_mask:0xf bound_ctrl:1
	s_nop 0
	v_add_f32_dpp v36, v36, v36 row_mirror row_mask:0xf bank_mask:0xf bound_ctrl:1
	v_pk_fma_f32 v[38:39], v[36:37], v[242:243], v[38:39] op_sel_hi:[0,1,1] neg_lo:[1,0,0] neg_hi:[1,0,0]
	v_pk_fma_f32 v[40:41], v[36:37], v[244:245], v[40:41] op_sel_hi:[0,1,1] neg_lo:[1,0,0] neg_hi:[1,0,0]
	v_pk_fma_f32 v[112:113], v[112:113], v[224:225], v[38:39]
	v_pk_fma_f32 v[114:115], v[114:115], v[226:227], v[40:41]
	global_store_dwordx4 v[2:3], v[112:115], off offset:3072
	v_pk_mul_f32 v[42:43], v[112:113], v[220:221]
	v_pk_fma_f32 v[42:43], v[114:115], v[222:223], v[42:43]
	v_add_f32_e32 v47, v42, v43
	s_nop 1
	v_add_f32_dpp v47, v47, v47 quad_perm:[1,0,3,2] row_mask:0xf bank_mask:0xf bound_ctrl:1
	s_nop 1
	v_add_f32_dpp v47, v47, v47 quad_perm:[2,3,0,1] row_mask:0xf bank_mask:0xf bound_ctrl:1
	s_nop 1
	v_add_f32_dpp v47, v47, v47 row_half_mirror row_mask:0xf bank_mask:0xf bound_ctrl:1
	s_nop 1
	v_add_f32_dpp v47, v47, v47 row_mirror row_mask:0xf bank_mask:0xf bound_ctrl:1
	v_cndmask_b32_e64 v48, v44, v45, s[8:9]
	v_cndmask_b32_e64 v48, v48, v46, s[12:13]
	s_nop 1
	v_cndmask_b32_e64 v48, v48, v47, s[14:15]
	s_and_saveexec_b64 s[6:7], s[18:19]
	ds_write_b32 v17, v48 offset:48
	s_mov_b64 exec, s[6:7]
	s_waitcnt vmcnt(10)
; __device__ __forceinline__ bf16_t f2bf(float f) { return (bf16_t)(cvt_pk_bf16(f, 0.f) & 0xffffu); }
; __device__ __forceinline__ void scan_wkv_sample(PP P, int l, const Ids I) {
;     ...
; #pragma unroll
;         for (int s = 0; s < 4; ++s) { const unsigned row = (unsigned)MTP + sb * 4 + s;
;             const float p = (S[0] * a_[s][0] + S[1] * a_[s][1]) + (S[2] * a_[s][2] + S[3] * a_[s][3]); const float sa = -row16_allsum(p);
; #pragma unroll
;             for (int j = 0; j < 4; ++j) S[j] = fmaf(S[j], __expf(-w_[s][j]), fmaf(sa, b_[s][j], v_[s] * k_[s][j]));
;             const float y = row16_allsum((S[0] * r_[s][0] + S[1] * r_[s][1]) + (S[2] * r_[s][2] + S[3] * r_[s][3]));
;             if (kseg == 0) ymix[row * 1024u + 512u + h * 64 + vrow] = f2bf(y); }
;         *(f32x4*)(out + O_SWKV + so) = S;
	v_lshlrev_b32_e32 v32, 16, v134
	s_nop 1
	v_mov_b32_dpp v24, v32 quad_perm:[0,0,0,0] row_mask:0xf bank_mask:0xf
	v_mov_b32_dpp v26, v32 quad_perm:[1,1,1,1] row_mask:0xf bank_mask:0xf
	v_mov_b32_dpp v28, v32 quad_perm:[2,2,2,2] row_mask:0xf bank_mask:0xf
	v_mov_b32_dpp v30, v32 quad_perm:[3,3,3,3] row_mask:0xf bank_mask:0xf
	v_pk_mul_f32 v[36:37], v[116:117], v[164:165]
	v_pk_mul_f32 v[38:39], v[24:25], v[160:161] op_sel_hi:[0,1]
	v_pk_fma_f32 v[36:37], v[118:119], v[166:167], v[36:37]
	v_pk_mul_f32 v[40:41], v[24:25], v[162:163] op_sel_hi:[0,1]
	v_add_f32_e32 v36, v36, v37
	s_nop 1
	v_add_f32_dpp v36, v36, v36 quad_perm:[1,0,3,2] row_mask:0xf bank_mask:0xf bound_ctrl:1
	s_nop 1
	v_add_f32_dpp v36, v36, v36 quad_perm:[2,3,0,1] row_mask:0xf bank_mask:0xf bound_ctrl:1
	s_nop 1
	v_add_f32_dpp v36, v36, v36 row_half_mirror row_mask:0xf bank_mask:0xf bound_ctrl:1
	s_nop 1
	v_add_f32_dpp v36, v36, v36 row_mirror row_mask:0xf bank_mask:0xf bound_ctrl:1
	v_pk_fma_f32 v[38:39], v[36:37], v[168:169], v[38:39] op_sel_hi:[0,1,1] neg_lo:[1,0,0] neg_hi:[1,0,0]
	v_pk_fma_f32 v[40:41], v[36:37], v[170:171], v[40:41] op_sel_hi:[0,1,1] neg_lo:[1,0,0] neg_hi:[1,0,0]
	v_pk_fma_f32 v[116:117], v[116:117], v[156:157], v[38:39]
	v_pk_fma_f32 v[118:119], v[118:119], v[158:159], v[40:41]
	v_pk_mul_f32 v[36:37], v[116:117], v[192:193]
	v_pk_mul_f32 v[42:43], v[116:117], v[152:153]
	v_pk_mul_f32 v[38:39], v[26:27], v[188:189] op_sel_hi:[0,1]
	v_pk_fma_f32 v[42:43], v[118:119], v[154:155], v[42:43]
	v_pk_fma_f32 v[36:37], v[118:119], v[194:195], v[36:37]
	v_add_f32_e32 v44, v42, v43
	v_pk_mul_f32 v[40:41], v[26:27], v[190:191] op_sel_hi:[0,1]
	v_add_f32_e32 v36, v36, v37
	v_add_f32_dpp v44, v44, v44 quad_perm:[1,0,3,2] row_mask:0xf bank_mask:0xf bound_ctrl:1
	s_nop 0
	v_add_f32_dpp v36, v36, v36 quad_perm:[1,0,3,2] row_mask:0xf bank_mask:0xf bound_ctrl:1
	v_add_f32_dpp v44, v44, v44 quad_perm:[2,3,0,1] row_mask:0xf bank_mask:0xf bound_ctrl:1
	s_nop 0
	v_add_f32_dpp v36, v36, v36 quad_perm:[2,3,0,1] row_mask:0xf bank_mask:0xf bound_ctrl:1
	v_add_f32_dpp v44, v44, v44 row_half_mirror row_mask:0xf bank_mask:0xf bound_ctrl:1
	s_nop 0
	v_add_f32_dpp v36, v36, v36 row_half_mirror row_mask:0xf bank_mask:0xf bound_ctrl:1
	v_add_f32_dpp v44, v44, v44 row_mirror row_mask:0xf bank_mask:0xf bound_ctrl:1
	s_nop 0
	v_add_f32_dpp v36, v36, v36 row_mirror row_mask:0xf bank_mask:0xf bound_ctrl:1
	v_pk_fma_f32 v[38:39], v[36:37], v[196:197], v[38:39] op_sel_hi:[0,1,1] neg_lo:[1,0,0] neg_hi:[1,0,0]
	v_pk_fma_f32 v[40:41], v[36:37], v[198:199], v[40:41] op_sel_hi:[0,1,1] neg_lo:[1,0,0] neg_hi:[1,0,0]
	v_pk_fma_f32 v[116:117], v[116:117], v[180:181], v[38:39]
	v_pk_fma_f32 v[118:119], v[118:119], v[182:183], v[40:41]
	v_pk_mul_f32 v[36:37], v[116:117], v[212:213]
	v_pk_mul_f32 v[42:43], v[116:117], v[176:177]
	v_pk_mul_f32 v[38:39], v[28:29], v[208:209] op_sel_hi:[0,1]
	v_pk_fma_f32 v[42:43], v[118:119], v[178:179], v[42:43]
	v_pk_fma_f32 v[36:37], v[118:119], v[214:215], v[36:37]
	v_add_f32_e32 v45, v42, v43
	v_pk_mul_f32 v[40:41], v[28:29], v[210:211] op_sel_hi:[0,1]
	v_add_f32_e32 v36, v36, v37
	v_add_f32_dpp v45, v45, v45 quad_perm:[1,0,3,2] row_mask:0xf bank_mask:0xf bound_ctrl:1
	s_nop 0
	v_add_f32_dpp v36, v36, v36 quad_perm:[1,0,3,2] row_mask:0xf bank_mask:0xf bound_ctrl:1
	v_add_f32_dpp v45, v45, v45 quad_perm:[2,3,0,1] row_mask:0xf bank_mask:0xf bound_ctrl:1
	s_nop 0
	v_add_f32_dpp v36, v36, v36 quad_perm:[2,3,0,1] row_mask:0xf bank_mask:0xf bound_ctrl:1
	v_add_f32_dpp v45, v45, v45 row_half_mirror row_mask:0xf bank_mask:0xf bound_ctrl:1
	s_nop 0
	v_add_f32_dpp v36, v36, v36 row_half_mirror row_mask:0xf bank_mask:0xf bound_ctrl:1
	v_add_f32_dpp v45, v45, v45 row_mirror row_mask:0xf bank_mask:0xf bound_ctrl:1
	s_nop 0
	v_add_f32_dpp v36, v36, v36 row_mirror row_mask:0xf bank_mask:0xf bound_ctrl:1
	v_pk_fma_f32 v[38:39], v[36:37], v[216:217], v[38:39] op_sel_hi:[0,1,1] neg_lo:[1,0,0] neg_hi:[1,0,0]
	v_pk_fma_f32 v[40:41], v[36:37], v[218:219], v[40:41] op_sel_hi:[0,1,1] neg_lo:[1,0,0] neg_hi:[1,0,0]
	v_pk_fma_f32 v[116:117], v[116:117], v[204:205], v[38:39]
	v_pk_fma_f32 v[118:119], v[118:119], v[206:207], v[40:41]
	v_pk_mul_f32 v[36:37], v[116:117], v[232:233]
	v_pk_mul_f32 v[42:43], v[116:117], v[200:201]
	v_pk_mul_f32 v[38:39], v[30:31], v[228:229] op_sel_hi:[0,1]
	v_pk_fma_f32 v[42:43], v[118:119], v[202:203], v[42:43]
	v_pk_fma_f32 v[36:37], v[118:119], v[234:235], v[36:37]
	v_add_f32_e32 v46, v42, v43
	v_pk_mul_f32 v[40:41], v[30:31], v[230:231] op_sel_hi:[0,1]
	v_add_f32_e32 v36, v36, v37
	v_add_f32_dpp v46, v46, v46 quad_perm:[1,0,3,2] row_mask:0xf bank_mask:0xf bound_ctrl:1
	s_nop 0
	v_add_f32_dpp v36, v36, v36 quad_perm:[1,0,3,2] row_mask:0xf bank_mask:0xf bound_ctrl:1
	v_add_f32_dpp v46, v46, v46 quad_perm:[2,3,0,1] row_mask:0xf bank_mask:0xf bound_ctrl:1
	s_nop 0
	v_add_f32_dpp v36, v36, v36 quad_perm:[2,3,0,1] row_mask:0xf bank_mask:0xf bound_ctrl:1
	v_add_f32_dpp v46, v46, v46 row_half_mirror row_mask:0xf bank_mask:0xf bound_ctrl:1
	s_nop 0
	v_add_f32_dpp v36, v36, v36 row_half_mirror row_mask:0xf bank_mask:0xf bound_ctrl:1
	v_add_f32_dpp v46, v46, v46 row_mirror row_mask:0xf bank_mask:0xf bound_ctrl:1
	s_nop 0
	v_add_f32_dpp v36, v36, v36 row_mirror row_mask:0xf bank_mask:0xf bound_ctrl:1
	v_pk_fma_f32 v[38:39], v[36:37], v[242:243], v[38:39] op_sel_hi:[0,1,1] neg_lo:[1,0,0] neg_hi:[1,0,0]
	v_pk_fma_f32 v[40:41], v[36:37], v[244:245], v[40:41] op_sel_hi:[0,1,1] neg_lo:[1,0,0] neg_hi:[1,0,0]
	v_pk_fma_f32 v[116:117], v[116:117], v[224:225], v[38:39]
	v_pk_fma_f32 v[118:119], v[118:119], v[226:227], v[40:41]
	global_store_dwordx4 v[6:7], v[116:119], off
	v_pk_mul_f32 v[42:43], v[116:117], v[220:221]
	v_pk_fma_f32 v[42:43], v[118:119], v[222:223], v[42:43]
	v_add_f32_e32 v47, v42, v43
	s_nop 1
	v_add_f32_dpp v47, v47, v47 quad_perm:[1,0,3,2] row_mask:0xf bank_mask:0xf bound_ctrl:1
	s_nop 1
	v_add_f32_dpp v47, v47, v47 quad_perm:[2,3,0,1] row_mask:0xf bank_mask:0xf bound_ctrl:1
	s_nop 1
	v_add_f32_dpp v47, v47, v47 row_half_mirror row_mask:0xf bank_mask:0xf bound_ctrl:1
	s_nop 1
	v_add_f32_dpp v47, v47, v47 row_mirror row_mask:0xf bank_mask:0xf bound_ctrl:1
	v_cndmask_b32_e64 v48, v44, v45, s[8:9]
	v_cndmask_b32_e64 v48, v48, v46, s[12:13]
	s_nop 1
	v_cndmask_b32_e64 v48, v48, v47, s[14:15]
	s_and_saveexec_b64 s[6:7], s[18:19]
	ds_write_b32 v17, v48 offset:64
	s_mov_b64 exec, s[6:7]
	s_waitcnt vmcnt(9)
; __device__ __forceinline__ bf16_t f2bf(float f) { return (bf16_t)(cvt_pk_bf16(f, 0.f) & 0xffffu); }
; __device__ __forceinline__ void scan_wkv_sample(PP P, int l, const Ids I) {
;     ...
; #pragma unroll
;         for (int s = 0; s < 4; ++s) { const unsigned row = (unsigned)MTP + sb * 4 + s;
;             const float p = (S[0] * a_[s][0] + S[1] * a_[s][1]) + (S[2] * a_[s][2] + S[3] * a_[s][3]); const float sa = -row16_allsum(p);
; #pragma unroll
;             for (int j = 0; j < 4; ++j) S[j] = fmaf(S[j], __expf(-w_[s][j]), fmaf(sa, b_[s][j], v_[s] * k_[s][j]));
;             const float y = row16_allsum((S[0] * r_[s][0] + S[1] * r_[s][1]) + (S[2] * r_[s][2] + S[3] * r_[s][3]));
;             if (kseg == 0) ymix[row * 1024u + 512u + h * 64 + vrow] = f2bf(y); }
;         *(f32x4*)(out + O_SWKV + so) = S;
	v_lshlrev_b32_e32 v32, 16, v135
	s_nop 1
	v_mov_b32_dpp v24, v32 quad_perm:[0,0,0,0] row_mask:0xf bank_mask:0xf
	v_mov_b32_dpp v26, v32 quad_perm:[1,1,1,1] row_mask:0xf bank_mask:0xf
	v_mov_b32_dpp v28, v32 quad_perm:[2,2,2,2] row_mask:0xf bank_mask:0xf
	v_mov_b32_dpp v30, v32 quad_perm:[3,3,3,3] row_mask:0xf bank_mask:0xf
	v_pk_mul_f32 v[36:37], v[120:121], v[164:165]
	v_pk_mul_f32 v[38:39], v[24:25], v[160:161] op_sel_hi:[0,1]
	v_pk_fma_f32 v[36:37], v[122:123], v[166:167], v[36:37]
	v_pk_mul_f32 v[40:41], v[24:25], v[162:163] op_sel_hi:[0,1]
	v_add_f32_e32 v36, v36, v37
	s_nop 1
	v_add_f32_dpp v36, v36, v36 quad_perm:[1,0,3,2] row_mask:0xf bank_mask:0xf bound_ctrl:1
	s_nop 1
	v_add_f32_dpp v36, v36, v36 quad_perm:[2,3,0,1] row_mask:0xf bank_mask:0xf bound_ctrl:1
	s_nop 1
	v_add_f32_dpp v36, v36, v36 row_half_mirror row_mask:0xf bank_mask:0xf bound_ctrl:1
	s_nop 1
	v_add_f32_dpp v36, v36, v36 row_mirror row_mask:0xf bank_mask:0xf bound_ctrl:1
	v_pk_fma_f32 v[38:39], v[36:37], v[168:169], v[38:39] op_sel_hi:[0,1,1] neg_lo:[1,0,0] neg_hi:[1,0,0]
	v_pk_fma_f32 v[40:41], v[36:37], v[170:171], v[40:41] op_sel_hi:[0,1,1] neg_lo:[1,0,0] neg_hi:[1,0,0]
	v_pk_fma_f32 v[120:121], v[120:121], v[156:157], v[38:39]
	v_pk_fma_f32 v[122:123], v[122:123], v[158:159], v[40:41]
	v_pk_mul_f32 v[36:37], v[120:121], v[192:193]
	v_pk_mul_f32 v[42:43], v[120:121], v[152:153]
	v_pk_mul_f32 v[38:39], v[26:27], v[188:189] op_sel_hi:[0,1]
	v_pk_fma_f32 v[42:43], v[122:123], v[154:155], v[42:43]
	v_pk_fma_f32 v[36:37], v[122:123], v[194:195], v[36:37]
	v_add_f32_e32 v44, v42, v43
	v_pk_mul_f32 v[40:41], v[26:27], v[190:191] op_sel_hi:[0,1]
	v_add_f32_e32 v36, v36, v37
	v_add_f32_dpp v44, v44, v44 quad_perm:[1,0,3,2] row_mask:0xf bank_mask:0xf bound_ctrl:1
	s_nop 0
	v_add_f32_dpp v36, v36, v36 quad_perm:[1,0,3,2] row_mask:0xf bank_mask:0xf bound_ctrl:1
	v_add_f32_dpp v44, v44, v44 quad_perm:[2,3,0,1] row_mask:0xf bank_mask:0xf bound_ctrl:1
	s_nop 0
	v_add_f32_dpp v36, v36, v36 quad_perm:[2,3,0,1] row_mask:0xf bank_mask:0xf bound_ctrl:1
	v_add_f32_dpp v44, v44, v44 row_half_mirror row_mask:0xf bank_mask:0xf bound_ctrl:1
	s_nop 0
	v_add_f32_dpp v36, v36, v36 row_half_mirror row_mask:0xf bank_mask:0xf bound_ctrl:1
	v_add_f32_dpp v44, v44, v44 row_mirror row_mask:0xf bank_mask:0xf bound_ctrl:1
	s_nop 0
	v_add_f32_dpp v36, v36, v36 row_mirror row_mask:0xf bank_mask:0xf bound_ctrl:1
	v_pk_fma_f32 v[38:39], v[36:37], v[196:197], v[38:39] op_sel_hi:[0,1,1] neg_lo:[1,0,0] neg_hi:[1,0,0]
	v_pk_fma_f32 v[40:41], v[36:37], v[198:199], v[40:41] op_sel_hi:[0,1,1] neg_lo:[1,0,0] neg_hi:[1,0,0]
	v_pk_fma_f32 v[120:121], v[120:121], v[180:181], v[38:39]
	v_pk_fma_f32 v[122:123], v[122:123], v[182:183], v[40:41]
	v_pk_mul_f32 v[36:37], v[120:121], v[212:213]
	v_pk_mul_f32 v[42:43], v[120:121], v[176:177]
	v_pk_mul_f32 v[38:39], v[28:29], v[208:209] op_sel_hi:[0,1]
	v_pk_fma_f32 v[42:43], v[122:123], v[178:179], v[42:43]
	v_pk_fma_f32 v[36:37], v[122:123], v[214:215], v[36:37]
	v_add_f32_e32 v45, v42, v43
	v_pk_mul_f32 v[40:41], v[28:29], v[210:211] op_sel_hi:[0,1]
	v_add_f32_e32 v36, v36, v37
	v_add_f32_dpp v45, v45, v45 quad_perm:[1,0,3,2] row_mask:0xf bank_mask:0xf bound_ctrl:1
	s_nop 0
	v_add_f32_dpp v36, v36, v36 quad_perm:[1,0,3,2] row_mask:0xf bank_mask:0xf bound_ctrl:1
	v_add_f32_dpp v45, v45, v45 quad_perm:[2,3,0,1] row_mask:0xf bank_mask:0xf bound_ctrl:1
	s_nop 0
	v_add_f32_dpp v36, v36, v36 quad_perm:[2,3,0,1] row_mask:0xf bank_mask:0xf bound_ctrl:1
	v_add_f32_dpp v45, v45, v45 row_half_mirror row_mask:0xf bank_mask:0xf bound_ctrl:1
	s_nop 0
	v_add_f32_dpp v36, v36, v36 row_half_mirror row_mask:0xf bank_mask:0xf bound_ctrl:1
	v_add_f32_dpp v45, v45, v45 row_mirror row_mask:0xf bank_mask:0xf bound_ctrl:1
	s_nop 0
	v_add_f32_dpp v36, v36, v36 row_mirror row_mask:0xf bank_mask:0xf bound_ctrl:1
	v_pk_fma_f32 v[38:39], v[36:37], v[216:217], v[38:39] op_sel_hi:[0,1,1] neg_lo:[1,0,0] neg_hi:[1,0,0]
	v_pk_fma_f32 v[40:41], v[36:37], v[218:219], v[40:41] op_sel_hi:[0,1,1] neg_lo:[1,0,0] neg_hi:[1,0,0]
	v_pk_fma_f32 v[120:121], v[120:121], v[204:205], v[38:39]
	v_pk_fma_f32 v[122:123], v[122:123], v[206:207], v[40:41]
	v_pk_mul_f32 v[36:37], v[120:121], v[232:233]
	v_pk_mul_f32 v[42:43], v[120:121], v[200:201]
	v_pk_mul_f32 v[38:39], v[30:31], v[228:229] op_sel_hi:[0,1]
	v_pk_fma_f32 v[42:43], v[122:123], v[202:203], v[42:43]
	v_pk_fma_f32 v[36:37], v[122:123], v[234:235], v[36:37]
	v_add_f32_e32 v46, v42, v43
	v_pk_mul_f32 v[40:41], v[30:31], v[230:231] op_sel_hi:[0,1]
	v_add_f32_e32 v36, v36, v37
	v_add_f32_dpp v46, v46, v46 quad_perm:[1,0,3,2] row_mask:0xf bank_mask:0xf bound_ctrl:1
	s_nop 0
	v_add_f32_dpp v36, v36, v36 quad_perm:[1,0,3,2] row_mask:0xf bank_mask:0xf bound_ctrl:1
	v_add_f32_dpp v46, v46, v46 quad_perm:[2,3,0,1] row_mask:0xf bank_mask:0xf bound_ctrl:1
	s_nop 0
	v_add_f32_dpp v36, v36, v36 quad_perm:[2,3,0,1] row_mask:0xf bank_mask:0xf bound_ctrl:1
	v_add_f32_dpp v46, v46, v46 row_half_mirror row_mask:0xf bank_mask:0xf bound_ctrl:1
	s_nop 0
	v_add_f32_dpp v36, v36, v36 row_half_mirror row_mask:0xf bank_mask:0xf bound_ctrl:1
	v_add_f32_dpp v46, v46, v46 row_mirror row_mask:0xf bank_mask:0xf bound_ctrl:1
	s_nop 0
	v_add_f32_dpp v36, v36, v36 row_mirror row_mask:0xf bank_mask:0xf bound_ctrl:1
	v_pk_fma_f32 v[38:39], v[36:37], v[242:243], v[38:39] op_sel_hi:[0,1,1] neg_lo:[1,0,0] neg_hi:[1,0,0]
	v_pk_fma_f32 v[40:41], v[36:37], v[244:245], v[40:41] op_sel_hi:[0,1,1] neg_lo:[1,0,0] neg_hi:[1,0,0]
	v_pk_fma_f32 v[120:121], v[120:121], v[224:225], v[38:39]
	v_pk_fma_f32 v[122:123], v[122:123], v[226:227], v[40:41]
	global_store_dwordx4 v[6:7], v[120:123], off offset:1024
	v_pk_mul_f32 v[42:43], v[120:121], v[220:221]
	v_pk_fma_f32 v[42:43], v[122:123], v[222:223], v[42:43]
	v_add_f32_e32 v47, v42, v43
	s_nop 1
	v_add_f32_dpp v47, v47, v47 quad_perm:[1,0,3,2] row_mask:0xf bank_mask:0xf bound_ctrl:1
	s_nop 1
	v_add_f32_dpp v47, v47, v47 quad_perm:[2,3,0,1] row_mask:0xf bank_mask:0xf bound_ctrl:1
	s_nop 1
	v_add_f32_dpp v47, v47, v47 row_half_mirror row_mask:0xf bank_mask:0xf bound_ctrl:1
	s_nop 1
	v_add_f32_dpp v47, v47, v47 row_mirror row_mask:0xf bank_mask:0xf bound_ctrl:1
	v_cndmask_b32_e64 v48, v44, v45, s[8:9]
	v_cndmask_b32_e64 v48, v48, v46, s[12:13]
	s_nop 1
	v_cndmask_b32_e64 v48, v48, v47, s[14:15]
	s_and_saveexec_b64 s[6:7], s[18:19]
	ds_write_b32 v17, v48 offset:80
	s_mov_b64 exec, s[6:7]
	s_waitcnt vmcnt(8)
; __device__ __forceinline__ bf16_t f2bf(float f) { return (bf16_t)(cvt_pk_bf16(f, 0.f) & 0xffffu); }
; __device__ __forceinline__ void scan_wkv_sample(PP P, int l, const Ids I) {
;     ...
; #pragma unroll
;         for (int s = 0; s < 4; ++s) { const unsigned row = (unsigned)MTP + sb * 4 + s;
;             const float p = (S[0] * a_[s][0] + S[1] * a_[s][1]) + (S[2] * a_[s][2] + S[3] * a_[s][3]); const float sa = -row16_allsum(p);
; #pragma unroll
;             for (int j = 0; j < 4; ++j) S[j] = fmaf(S[j], __expf(-w_[s][j]), fmaf(sa, b_[s][j], v_[s] * k_[s][j]));
;             const float y = row16_allsum((S[0] * r_[s][0] + S[1] * r_[s][1]) + (S[2] * r_[s][2] + S[3] * r_[s][3]));
;             if (kseg == 0) ymix[row * 1024u + 512u + h * 64 + vrow] = f2bf(y); }
;         *(f32x4*)(out + O_SWKV + so) = S;
	v_lshlrev_b32_e32 v32, 16, v136
	s_nop 1
	v_mov_b32_dpp v24, v32 quad_perm:[0,0,0,0] row_mask:0xf bank_mask:0xf
	v_mov_b32_dpp v26, v32 quad_perm:[1,1,1,1] row_mask:0xf bank_mask:0xf
	v_mov_b32_dpp v28, v32 quad_perm:[2,2,2,2] row_mask:0xf bank_mask:0xf
	v_mov_b32_dpp v30, v32 quad_perm:[3,3,3,3] row_mask:0xf bank_mask:0xf
	v_pk_mul_f32 v[36:37], v[124:125], v[164:165]
	v_pk_mul_f32 v[38:39], v[24:25], v[160:161] op_sel_hi:[0,1]
	v_pk_fma_f32 v[36:37], v[126:127], v[166:167], v[36:37]
	v_pk_mul_f32 v[40:41], v[24:25], v[162:163] op_sel_hi:[0,1]
	v_add_f32_e32 v36, v36, v37
	s_nop 1
	v_add_f32_dpp v36, v36, v36 quad_perm:[1,0,3,2] row_mask:0xf bank_mask:0xf bound_ctrl:1
	s_nop 1
	v_add_f32_dpp v36, v36, v36 quad_perm:[2,3,0,1] row_mask:0xf bank_mask:0xf bound_ctrl:1
	s_nop 1
	v_add_f32_dpp v36, v36, v36 row_half_mirror row_mask:0xf bank_mask:0xf bound_ctrl:1
	s_nop 1
	v_add_f32_dpp v36, v36, v36 row_mirror row_mask:0xf bank_mask:0xf bound_ctrl:1
	v_pk_fma_f32 v[38:39], v[36:37], v[168:169], v[38:39] op_sel_hi:[0,1,1] neg_lo:[1,0,0] neg_hi:[1,0,0]
	v_pk_fma_f32 v[40:41], v[36:37], v[170:171], v[40:41] op_sel_hi:[0,1,1] neg_lo:[1,0,0] neg_hi:[1,0,0]
	v_pk_fma_f32 v[124:125], v[124:125], v[156:157], v[38:39]
	v_pk_fma_f32 v[126:127], v[126:127], v[158:159], v[40:41]
	v_pk_mul_f32 v[36:37], v[124:125], v[192:193]
	v_pk_mul_f32 v[42:43], v[124:125], v[152:153]
	v_pk_mul_f32 v[38:39], v[26:27], v[188:189] op_sel_hi:[0,1]
	v_pk_fma_f32 v[42:43], v[126:127], v[154:155], v[42:43]
	v_pk_fma_f32 v[36:37], v[126:127], v[194:195], v[36:37]
	v_add_f32_e32 v44, v42, v43
	v_pk_mul_f32 v[40:41], v[26:27], v[190:191] op_sel_hi:[0,1]
	v_add_f32_e32 v36, v36, v37
	v_add_f32_dpp v44, v44, v44 quad_perm:[1,0,3,2] row_mask:0xf bank_mask:0xf bound_ctrl:1
	s_nop 0
	v_add_f32_dpp v36, v36, v36 quad_perm:[1,0,3,2] row_mask:0xf bank_mask:0xf bound_ctrl:1
	v_add_f32_dpp v44, v44, v44 quad_perm:[2,3,0,1] row_mask:0xf bank_mask:0xf bound_ctrl:1
	s_nop 0
	v_add_f32_dpp v36, v36, v36 quad_perm:[2,3,0,1] row_mask:0xf bank_mask:0xf bound_ctrl:1
	v_add_f32_dpp v44, v44, v44 row_half_mirror row_mask:0xf bank_mask:0xf bound_ctrl:1
	s_nop 0
	v_add_f32_dpp v36, v36, v36 row_half_mirror row_mask:0xf bank_mask:0xf bound_ctrl:1
	v_add_f32_dpp v44, v44, v44 row_mirror row_mask:0xf bank_mask:0xf bound_ctrl:1
	s_nop 0
	v_add_f32_dpp v36, v36, v36 row_mirror row_mask:0xf bank_mask:0xf bound_ctrl:1
	v_pk_fma_f32 v[38:39], v[36:37], v[196:197], v[38:39] op_sel_hi:[0,1,1] neg_lo:[1,0,0] neg_hi:[1,0,0]
	v_pk_fma_f32 v[40:41], v[36:37], v[198:199], v[40:41] op_sel_hi:[0,1,1] neg_lo:[1,0,0] neg_hi:[1,0,0]
	v_pk_fma_f32 v[124:125], v[124:125], v[180:181], v[38:39]
	v_pk_fma_f32 v[126:127], v[126:127], v[182:183], v[40:41]
	v_pk_mul_f32 v[36:37], v[124:125], v[212:213]
	v_pk_mul_f32 v[42:43], v[124:125], v[176:177]
	v_pk_mul_f32 v[38:39], v[28:29], v[208:209] op_sel_hi:[0,1]
	v_pk_fma_f32 v[42:43], v[126:127], v[178:179], v[42:43]
	v_pk_fma_f32 v[36:37], v[126:127], v[214:215], v[36:37]
	v_add_f32_e32 v45, v42, v43
	v_pk_mul_f32 v[40:41], v[28:29], v[210:211] op_sel_hi:[0,1]
	v_add_f32_e32 v36, v36, v37
	v_add_f32_dpp v45, v45, v45 quad_perm:[1,0,3,2] row_mask:0xf bank_mask:0xf bound_ctrl:1
	s_nop 0
	v_add_f32_dpp v36, v36, v36 quad_perm:[1,0,3,2] row_mask:0xf bank_mask:0xf bound_ctrl:1
	v_add_f32_dpp v45, v45, v45 quad_perm:[2,3,0,1] row_mask:0xf bank_mask:0xf bound_ctrl:1
	s_nop 0
	v_add_f32_dpp v36, v36, v36 quad_perm:[2,3,0,1] row_mask:0xf bank_mask:0xf bound_ctrl:1
	v_add_f32_dpp v45, v45, v45 row_half_mirror row_mask:0xf bank_mask:0xf bound_ctrl:1
	s_nop 0
	v_add_f32_dpp v36, v36, v36 row_half_mirror row_mask:0xf bank_mask:0xf bound_ctrl:1
	v_add_f32_dpp v45, v45, v45 row_mirror row_mask:0xf bank_mask:0xf bound_ctrl:1
	s_nop 0
	v_add_f32_dpp v36, v36, v36 row_mirror row_mask:0xf bank_mask:0xf bound_ctrl:1
	v_pk_fma_f32 v[38:39], v[36:37], v[216:217], v[38:39] op_sel_hi:[0,1,1] neg_lo:[1,0,0] neg_hi:[1,0,0]
	v_pk_fma_f32 v[40:41], v[36:37], v[218:219], v[40:41] op_sel_hi:[0,1,1] neg_lo:[1,0,0] neg_hi:[1,0,0]
	v_pk_fma_f32 v[124:125], v[124:125], v[204:205], v[38:39]
	v_pk_fma_f32 v[126:127], v[126:127], v[206:207], v[40:41]
	v_pk_mul_f32 v[36:37], v[124:125], v[232:233]
	v_pk_mul_f32 v[42:43], v[124:125], v[200:201]
	v_pk_mul_f32 v[38:39], v[30:31], v[228:229] op_sel_hi:[0,1]
	v_pk_fma_f32 v[42:43], v[126:127], v[202:203], v[42:43]
	v_pk_fma_f32 v[36:37], v[126:127], v[234:235], v[36:37]
	v_add_f32_e32 v46, v42, v43
	v_pk_mul_f32 v[40:41], v[30:31], v[230:231] op_sel_hi:[0,1]
	v_add_f32_e32 v36, v36, v37
	v_add_f32_dpp v46, v46, v46 quad_perm:[1,0,3,2] row_mask:0xf bank_mask:0xf bound_ctrl:1
	s_nop 0
	v_add_f32_dpp v36, v36, v36 quad_perm:[1,0,3,2] row_mask:0xf bank_mask:0xf bound_ctrl:1
	v_add_f32_dpp v46, v46, v46 quad_perm:[2,3,0,1] row_mask:0xf bank_mask:0xf bound_ctrl:1
	s_nop 0
	v_add_f32_dpp v36, v36, v36 quad_perm:[2,3,0,1] row_mask:0xf bank_mask:0xf bound_ctrl:1
	v_add_f32_dpp v46, v46, v46 row_half_mirror row_mask:0xf bank_mask:0xf bound_ctrl:1
	s_nop 0
	v_add_f32_dpp v36, v36, v36 row_half_mirror row_mask:0xf bank_mask:0xf bound_ctrl:1
	v_add_f32_dpp v46, v46, v46 row_mirror row_mask:0xf bank_mask:0xf bound_ctrl:1
	s_nop 0
	v_add_f32_dpp v36, v36, v36 row_mirror row_mask:0xf bank_mask:0xf bound_ctrl:1
	v_pk_fma_f32 v[38:39], v[36:37], v[242:243], v[38:39] op_sel_hi:[0,1,1] neg_lo:[1,0,0] neg_hi:[1,0,0]
	v_pk_fma_f32 v[40:41], v[36:37], v[244:245], v[40:41] op_sel_hi:[0,1,1] neg_lo:[1,0,0] neg_hi:[1,0,0]
	v_pk_fma_f32 v[124:125], v[124:125], v[224:225], v[38:39]
	v_pk_fma_f32 v[126:127], v[126:127], v[226:227], v[40:41]
	global_store_dwordx4 v[6:7], v[124:127], off offset:2048
	v_pk_mul_f32 v[42:43], v[124:125], v[220:221]
	v_pk_fma_f32 v[42:43], v[126:127], v[222:223], v[42:43]
	v_add_f32_e32 v47, v42, v43
	s_nop 1
	v_add_f32_dpp v47, v47, v47 quad_perm:[1,0,3,2] row_mask:0xf bank_mask:0xf bound_ctrl:1
	s_nop 1
	v_add_f32_dpp v47, v47, v47 quad_perm:[2,3,0,1] row_mask:0xf bank_mask:0xf bound_ctrl:1
	s_nop 1
	v_add_f32_dpp v47, v47, v47 row_half_mirror row_mask:0xf bank_mask:0xf bound_ctrl:1
	s_nop 1
	v_add_f32_dpp v47, v47, v47 row_mirror row_mask:0xf bank_mask:0xf bound_ctrl:1
	v_cndmask_b32_e64 v48, v44, v45, s[8:9]
	v_cndmask_b32_e64 v48, v48, v46, s[12:13]
	s_nop 1
	v_cndmask_b32_e64 v48, v48, v47, s[14:15]
	s_and_saveexec_b64 s[6:7], s[18:19]
	ds_write_b32 v17, v48 offset:96
	s_mov_b64 exec, s[6:7]
	s_waitcnt vmcnt(7)
; __device__ __forceinline__ bf16_t f2bf(float f) { return (bf16_t)(cvt_pk_bf16(f, 0.f) & 0xffffu); }
; __device__ __forceinline__ void scan_wkv_sample(PP P, int l, const Ids I) {
;     ...
; #pragma unroll
;         for (int s = 0; s < 4; ++s) { const unsigned row = (unsigned)MTP + sb * 4 + s;
;             const float p = (S[0] * a_[s][0] + S[1] * a_[s][1]) + (S[2] * a_[s][2] + S[3] * a_[s][3]); const float sa = -row16_allsum(p);
; #pragma unroll
;             for (int j = 0; j < 4; ++j) S[j] = fmaf(S[j], __expf(-w_[s][j]), fmaf(sa, b_[s][j], v_[s] * k_[s][j]));
;             const float y = row16_allsum((S[0] * r_[s][0] + S[1] * r_[s][1]) + (S[2] * r_[s][2] + S[3] * r_[s][3]));
;             if (kseg == 0) ymix[row * 1024u + 512u + h * 64 + vrow] = f2bf(y); }
;         *(f32x4*)(out + O_SWKV + so) = S;
	v_lshlrev_b32_e32 v32, 16, v137
	s_nop 1
	v_mov_b32_dpp v24, v32 quad_perm:[0,0,0,0] row_mask:0xf bank_mask:0xf
	v_mov_b32_dpp v26, v32 quad_perm:[1,1,1,1] row_mask:0xf bank_mask:0xf
	v_mov_b32_dpp v28, v32 quad_perm:[2,2,2,2] row_mask:0xf bank_mask:0xf
	v_mov_b32_dpp v30, v32 quad_perm:[3,3,3,3] row_mask:0xf bank_mask:0xf
	v_pk_mul_f32 v[36:37], v[128:129], v[164:165]
	v_pk_mul_f32 v[38:39], v[24:25], v[160:161] op_sel_hi:[0,1]
	v_pk_fma_f32 v[36:37], v[130:131], v[166:167], v[36:37]
	v_pk_mul_f32 v[40:41], v[24:25], v[162:163] op_sel_hi:[0,1]
	v_add_f32_e32 v36, v36, v37
	s_nop 1
	v_add_f32_dpp v36, v36, v36 quad_perm:[1,0,3,2] row_mask:0xf bank_mask:0xf bound_ctrl:1
	s_nop 1
	v_add_f32_dpp v36, v36, v36 quad_perm:[2,3,0,1] row_mask:0xf bank_mask:0xf bound_ctrl:1
	s_nop 1
	v_add_f32_dpp v36, v36, v36 row_half_mirror row_mask:0xf bank_mask:0xf bound_ctrl:1
	s_nop 1
	v_add_f32_dpp v36, v36, v36 row_mirror row_mask:0xf bank_mask:0xf bound_ctrl:1
	v_pk_fma_f32 v[38:39], v[36:37], v[168:169], v[38:39] op_sel_hi:[0,1,1] neg_lo:[1,0,0] neg_hi:[1,0,0]
	v_pk_fma_f32 v[40:41], v[36:37], v[170:171], v[40:41] op_sel_hi:[0,1,1] neg_lo:[1,0,0] neg_hi:[1,0,0]
	v_pk_fma_f32 v[128:129], v[128:129], v[156:157], v[38:39]
	v_pk_fma_f32 v[130:131], v[130:131], v[158:159], v[40:41]
	v_pk_mul_f32 v[36:37], v[128:129], v[192:193]
	v_pk_mul_f32 v[42:43], v[128:129], v[152:153]
	v_pk_mul_f32 v[38:39], v[26:27], v[188:189] op_sel_hi:[0,1]
	v_pk_fma_f32 v[42:43], v[130:131], v[154:155], v[42:43]
	v_pk_fma_f32 v[36:37], v[130:131], v[194:195], v[36:37]
	v_add_f32_e32 v44, v42, v43
	v_pk_mul_f32 v[40:41], v[26:27], v[190:191] op_sel_hi:[0,1]
	v_add_f32_e32 v36, v36, v37
	v_add_f32_dpp v44, v44, v44 quad_perm:[1,0,3,2] row_mask:0xf bank_mask:0xf bound_ctrl:1
	s_nop 0
	v_add_f32_dpp v36, v36, v36 quad_perm:[1,0,3,2] row_mask:0xf bank_mask:0xf bound_ctrl:1
	v_add_f32_dpp v44, v44, v44 quad_perm:[2,3,0,1] row_mask:0xf bank_mask:0xf bound_ctrl:1
	s_nop 0
	v_add_f32_dpp v36, v36, v36 quad_perm:[2,3,0,1] row_mask:0xf bank_mask:0xf bound_ctrl:1
	v_add_f32_dpp v44, v44, v44 row_half_mirror row_mask:0xf bank_mask:0xf bound_ctrl:1
	s_nop 0
	v_add_f32_dpp v36, v36, v36 row_half_mirror row_mask:0xf bank_mask:0xf bound_ctrl:1
	v_add_f32_dpp v44, v44, v44 row_mirror row_mask:0xf bank_mask:0xf bound_ctrl:1
	s_nop 0
	v_add_f32_dpp v36, v36, v36 row_mirror row_mask:0xf bank_mask:0xf bound_ctrl:1
	v_pk_fma_f32 v[38:39], v[36:37], v[196:197], v[38:39] op_sel_hi:[0,1,1] neg_lo:[1,0,0] neg_hi:[1,0,0]
	v_pk_fma_f32 v[40:41], v[36:37], v[198:199], v[40:41] op_sel_hi:[0,1,1] neg_lo:[1,0,0] neg_hi:[1,0,0]
	v_pk_fma_f32 v[128:129], v[128:129], v[180:181], v[38:39]
	v_pk_fma_f32 v[130:131], v[130:131], v[182:183], v[40:41]
	v_pk_mul_f32 v[36:37], v[128:129], v[212:213]
	v_pk_mul_f32 v[42:43], v[128:129], v[176:177]
	v_pk_mul_f32 v[38:39], v[28:29], v[208:209] op_sel_hi:[0,1]
	v_pk_fma_f32 v[42:43], v[130:131], v[178:179], v[42:43]
	v_pk_fma_f32 v[36:37], v[130:131], v[214:215], v[36:37]
	v_add_f32_e32 v45, v42, v43
	v_pk_mul_f32 v[40:41], v[28:29], v[210:211] op_sel_hi:[0,1]
	v_add_f32_e32 v36, v36, v37
	v_add_f32_dpp v45, v45, v45 quad_perm:[1,0,3,2] row_mask:0xf bank_mask:0xf bound_ctrl:1
	s_nop 0
	v_add_f32_dpp v36, v36, v36 quad_perm:[1,0,3,2] row_mask:0xf bank_mask:0xf bound_ctrl:1
	v_add_f32_dpp v45, v45, v45 quad_perm:[2,3,0,1] row_mask:0xf bank_mask:0xf bound_ctrl:1
	s_nop 0
	v_add_f32_dpp v36, v36, v36 quad_perm:[2,3,0,1] row_mask:0xf bank_mask:0xf bound_ctrl:1
	v_add_f32_dpp v45, v45, v45 row_half_mirror row_mask:0xf bank_mask:0xf bound_ctrl:1
	s_nop 0
	v_add_f32_dpp v36, v36, v36 row_half_mirror row_mask:0xf bank_mask:0xf bound_ctrl:1
	v_add_f32_dpp v45, v45, v45 row_mirror row_mask:0xf bank_mask:0xf bound_ctrl:1
	s_nop 0
	v_add_f32_dpp v36, v36, v36 row_mirror row_mask:0xf bank_mask:0xf bound_ctrl:1
	v_pk_fma_f32 v[38:39], v[36:37], v[216:217], v[38:39] op_sel_hi:[0,1,1] neg_lo:[1,0,0] neg_hi:[1,0,0]
	v_pk_fma_f32 v[40:41], v[36:37], v[218:219], v[40:41] op_sel_hi:[0,1,1] neg_lo:[1,0,0] neg_hi:[1,0,0]
	v_pk_fma_f32 v[128:129], v[128:129], v[204:205], v[38:39]
	v_pk_fma_f32 v[130:131], v[130:131], v[206:207], v[40:41]
	v_pk_mul_f32 v[36:37], v[128:129], v[232:233]
	v_pk_mul_f32 v[42:43], v[128:129], v[200:201]
	v_pk_mul_f32 v[38:39], v[30:31], v[228:229] op_sel_hi:[0,1]
	v_pk_fma_f32 v[42:43], v[130:131], v[202:203], v[42:43]
	v_pk_fma_f32 v[36:37], v[130:131], v[234:235], v[36:37]
	v_add_f32_e32 v46, v42, v43
	v_pk_mul_f32 v[40:41], v[30:31], v[230:231] op_sel_hi:[0,1]
	v_add_f32_e32 v36, v36, v37
	v_add_f32_dpp v46, v46, v46 quad_perm:[1,0,3,2] row_mask:0xf bank_mask:0xf bound_ctrl:1
	s_nop 0
	v_add_f32_dpp v36, v36, v36 quad_perm:[1,0,3,2] row_mask:0xf bank_mask:0xf bound_ctrl:1
	v_add_f32_dpp v46, v46, v46 quad_perm:[2,3,0,1] row_mask:0xf bank_mask:0xf bound_ctrl:1
	s_nop 0
	v_add_f32_dpp v36, v36, v36 quad_perm:[2,3,0,1] row_mask:0xf bank_mask:0xf bound_ctrl:1
	v_add_f32_dpp v46, v46, v46 row_half_mirror row_mask:0xf bank_mask:0xf bound_ctrl:1
	s_nop 0
	v_add_f32_dpp v36, v36, v36 row_half_mirror row_mask:0xf bank_mask:0xf bound_ctrl:1
	v_add_f32_dpp v46, v46, v46 row_mirror row_mask:0xf bank_mask:0xf bound_ctrl:1
	s_nop 0
	v_add_f32_dpp v36, v36, v36 row_mirror row_mask:0xf bank_mask:0xf bound_ctrl:1
	v_pk_fma_f32 v[38:39], v[36:37], v[242:243], v[38:39] op_sel_hi:[0,1,1] neg_lo:[1,0,0] neg_hi:[1,0,0]
	v_pk_fma_f32 v[40:41], v[36:37], v[244:245], v[40:41] op_sel_hi:[0,1,1] neg_lo:[1,0,0] neg_hi:[1,0,0]
	v_pk_fma_f32 v[128:129], v[128:129], v[224:225], v[38:39]
	v_pk_fma_f32 v[130:131], v[130:131], v[226:227], v[40:41]
	global_store_dwordx4 v[6:7], v[128:131], off offset:3072
	v_pk_mul_f32 v[42:43], v[128:129], v[220:221]
	v_pk_fma_f32 v[42:43], v[130:131], v[222:223], v[42:43]
	v_add_f32_e32 v47, v42, v43
	s_nop 1
	v_add_f32_dpp v47, v47, v47 quad_perm:[1,0,3,2] row_mask:0xf bank_mask:0xf bound_ctrl:1
	s_nop 1
	v_add_f32_dpp v47, v47, v47 quad_perm:[2,3,0,1] row_mask:0xf bank_mask:0xf bound_ctrl:1
	s_nop 1
	v_add_f32_dpp v47, v47, v47 row_half_mirror row_mask:0xf bank_mask:0xf bound_ctrl:1
	s_nop 1
	v_add_f32_dpp v47, v47, v47 row_mirror row_mask:0xf bank_mask:0xf bound_ctrl:1
	v_cndmask_b32_e64 v48, v44, v45, s[8:9]
	v_cndmask_b32_e64 v48, v48, v46, s[12:13]
	s_nop 1
	v_cndmask_b32_e64 v48, v48, v47, s[14:15]
	s_and_saveexec_b64 s[6:7], s[18:19]
	ds_write_b32 v17, v48 offset:112
	s_mov_b64 exec, s[6:7]
	s_waitcnt lgkmcnt(0)
	s_and_saveexec_b64 s[6:7], s[0:1]
	ds_read_b128 v[20:23], v19
	ds_read_b128 v[24:27], v19 offset:16
	s_waitcnt lgkmcnt(0)
	v_cvt_pk_bf16_f32 v20, v20, v21
	v_cvt_pk_bf16_f32 v21, v22, v23
	v_cvt_pk_bf16_f32 v22, v24, v25
	v_cvt_pk_bf16_f32 v23, v26, v27
	global_store_dwordx4 v[10:11], v[20:23], off
	s_mov_b64 exec, s[6:7]
	s_branch .LBB0_754
	s_nop 0
	s_nop 0
	s_nop 0
	s_nop 0
	s_nop 0
	s_nop 0
	s_nop 0
	s_nop 0
	s_nop 0
	s_nop 0
	s_nop 0
	s_nop 0
	s_nop 0
	s_nop 0
	s_nop 0
	s_nop 0
	s_nop 0
	s_nop 0
	s_nop 0
	s_nop 0
	s_nop 0
	s_nop 0
